# FFN_IN: row-ss loads issued at k-loop head into free VGPRs, reduction+bpermute interleaved into the last MFMA block (no load latency in epilogue)
# speedup vs baseline: 1.0095x; 1.0095x over previous
.LBB0_266:
	v_add_u32_e32 v164, s76, v173
	v_and_b32_e32 v222, 31, v199
	v_bfe_u32 v223, v199, 5, 1
	v_lshlrev_b32_e32 v224, 2, v223
	v_sub_u32_e32 v222, v222, v224
	v_add_u32_e32 v224, s76, v173
	v_add_lshl_u32 v222, v222, v224, 2
	v_lshlrev_b32_e32 v223, 4, v223
	global_load_dword v194, v222, s[18:19]
	v_add_u32_e32 v224, 0x10000, v222
	global_load_dword v195, v224, s[18:19]
	v_add_u32_e32 v224, 0x20000, v222
	global_load_dword v196, v224, s[18:19]
	v_add_u32_e32 v224, 0x30000, v222
	global_load_dword v197, v224, s[18:19]
	v_add_u32_e32 v224, 0x40000, v222
	global_load_dword v202, v224, s[18:19]
	v_add_u32_e32 v224, 0x50000, v222
	global_load_dword v203, v224, s[18:19]
	v_add_u32_e32 v224, 0x60000, v222
	global_load_dword v204, v224, s[18:19]
	v_add_u32_e32 v224, 0x70000, v222
	global_load_dword v205, v224, s[18:19]
	s_waitcnt vmcnt(0)
	v_add_f32_e32 v194, v194, v195
	v_add_f32_e32 v196, v196, v197
	v_add_f32_e32 v202, v202, v203
	v_add_f32_e32 v204, v204, v205
	v_add_f32_e32 v194, v194, v196
	v_add_f32_e32 v202, v202, v204
	v_add_f32_e32 v194, v194, v202
	v_fmamk_f32 v194, v194, 0x3a800000, v209
	v_rsq_f32_e32 v194, v194
	s_nop 1
	ds_bpermute_b32 v225, v223, v194
	ds_bpermute_b32 v230, v223, v194 offset:4
	ds_bpermute_b32 v231, v223, v194 offset:8
	ds_bpermute_b32 v232, v223, v194 offset:12
	ds_bpermute_b32 v233, v223, v194 offset:32
	ds_bpermute_b32 v234, v223, v194 offset:36
	ds_bpermute_b32 v235, v223, v194 offset:40
	ds_bpermute_b32 v236, v223, v194 offset:44
	ds_bpermute_b32 v237, v223, v194 offset:64
	ds_bpermute_b32 v238, v223, v194 offset:68
	ds_bpermute_b32 v239, v223, v194 offset:72
	ds_bpermute_b32 v240, v223, v194 offset:76
	ds_bpermute_b32 v241, v223, v194 offset:96
	ds_bpermute_b32 v242, v223, v194 offset:100
	ds_bpermute_b32 v243, v223, v194 offset:104
	ds_bpermute_b32 v244, v223, v194 offset:108
	s_waitcnt lgkmcnt(0)
	s_lshl_b64 s[80:81], s[80:81], 2
	s_add_u32 s80, s84, s80
	s_addc_u32 s81, s85, s81
	s_cmp_gt_i32 s95, 23
	v_or_b32_e32 v92, 16, v164
	v_ashrrev_i32_e32 v93, 31, v92
	v_lshl_add_u64 v[92:93], v[92:93], 2, s[18:19]
	v_or_b32_e32 v68, 24, v164
	v_add_co_u32_e32 v94, vcc, s91, v92
	v_ashrrev_i32_e32 v69, 31, v68
	s_nop 0
	v_addc_co_u32_e32 v95, vcc, 0, v93, vcc
	v_lshl_add_u64 v[80:81], v[68:69], 2, s[18:19]
	v_add_co_u32_e32 v88, vcc, s90, v80
	s_nop 1
	v_addc_co_u32_e32 v89, vcc, 0, v81, vcc
	v_add_co_u32_e32 v84, vcc, s91, v80
	s_nop 1
	v_addc_co_u32_e32 v85, vcc, 0, v81, vcc
	v_add_co_u32_e32 v80, vcc, s92, v80
	s_nop 1
	v_addc_co_u32_e32 v81, vcc, 0, v81, vcc
	v_or_b32_e32 v76, s78, v156
	v_ashrrev_i32_e32 v77, 31, v76
	v_lshl_add_u64 v[64:65], v[76:77], 2, s[80:81]
	global_load_dword v81, v[64:65], off
	global_load_dword v80, v[64:65], off offset:128
	global_load_dword v82, v[64:65], off offset:256
	global_load_dword v83, v[64:65], off offset:384
	v_mov_b32_e32 v65, v48
	v_mov_b32_e32 v48, v33
	v_mov_b32_e32 v33, v50
	v_mov_b32_e32 v50, v35
	s_mov_b64 s[80:81], -1
	v_mov_b32_e32 v94, v234
	v_mov_b32_e32 v96, v235
	v_mov_b32_e32 v98, v236
	v_mov_b32_e32 v100, v237
	v_mov_b32_e32 v84, v225
	v_mov_b32_e32 v102, v238
	v_mov_b32_e32 v86, v230
	v_mov_b32_e32 v104, v239
	v_mov_b32_e32 v88, v231
	v_mov_b32_e32 v106, v240
	v_mov_b32_e32 v90, v232
	v_mov_b32_e32 v108, v241
	v_mov_b32_e32 v92, v233
	v_mov_b32_e32 v110, v242
	v_mov_b32_e32 v112, v243
	v_mov_b32_e32 v114, v244
	v_mov_b32_e32 v64, v32
	v_mov_b32_e32 v32, v34
	s_waitcnt vmcnt(2)
	v_pk_fma_f32 v[72:73], v[32:33], v[88:89], v[80:81] op_sel_hi:[1,0,1]
	v_mov_b32_e32 v32, v36
	v_mov_b32_e32 v33, v52
	v_pk_fma_f32 v[68:69], v[32:33], v[92:93], v[80:81] op_sel_hi:[1,0,1]
	v_mov_b32_e32 v32, v38
	v_mov_b32_e32 v33, v54
	v_pk_fma_f32 v[78:79], v[64:65], v[84:85], v[80:81] op_sel_hi:[1,0,1]
	v_mov_b32_e32 v52, v37
	v_pk_fma_f32 v[64:65], v[32:33], v[96:97], v[80:81] op_sel_hi:[1,0,1]
	v_mov_b32_e32 v32, v40
	v_mov_b32_e32 v33, v56
	v_pk_fma_f32 v[66:67], v[52:53], v[94:95], v[80:81] op_sel_hi:[1,0,1]
	v_pk_fma_f32 v[52:53], v[32:33], v[100:101], v[80:81] op_sel_hi:[1,0,1]
	v_mov_b32_e32 v32, v42
	v_mov_b32_e32 v33, v58
	v_pk_fma_f32 v[74:75], v[48:49], v[86:87], v[80:81] op_sel_hi:[1,0,1]
	v_pk_fma_f32 v[48:49], v[32:33], v[104:105], v[80:81] op_sel_hi:[1,0,1]
	v_mov_b32_e32 v32, v44
	v_mov_b32_e32 v33, v60
	v_mov_b32_e32 v54, v39
	v_mov_b32_e32 v56, v41
	v_mov_b32_e32 v58, v43
	v_pk_fma_f32 v[38:39], v[32:33], v[108:109], v[80:81] op_sel_hi:[1,0,1]
	v_mov_b32_e32 v60, v45
	v_mov_b32_e32 v32, v46
	v_mov_b32_e32 v33, v62
	v_mov_b32_e32 v62, v47
	v_pk_fma_f32 v[70:71], v[50:51], v[90:91], v[80:81] op_sel_hi:[1,0,1]
	v_pk_fma_f32 v[54:55], v[54:55], v[98:99], v[80:81] op_sel_hi:[1,0,1]
	v_pk_fma_f32 v[50:51], v[56:57], v[102:103], v[80:81] op_sel_hi:[1,0,1]
	v_pk_fma_f32 v[40:41], v[58:59], v[106:107], v[80:81] op_sel_hi:[1,0,1]
	v_pk_fma_f32 v[36:37], v[60:61], v[110:111], v[80:81] op_sel_hi:[1,0,1]
	v_pk_fma_f32 v[34:35], v[32:33], v[112:113], v[80:81] op_sel_hi:[1,0,1]
	v_pk_fma_f32 v[32:33], v[62:63], v[114:115], v[80:81] op_sel_hi:[1,0,1]
	s_waitcnt vmcnt(1)
	v_fma_f32 v57, v16, v84, v82
	v_fma_f32 v47, v17, v86, v82
	v_fma_f32 v46, v18, v88, v82
	v_fma_f32 v45, v19, v90, v82
	v_fma_f32 v44, v20, v92, v82
	v_fma_f32 v43, v21, v94, v82
	v_fma_f32 v42, v22, v96, v82
	v_fma_f32 v23, v23, v98, v82
	v_fma_f32 v22, v24, v100, v82
	v_fma_f32 v21, v25, v102, v82
	v_fma_f32 v20, v26, v104, v82
	v_fma_f32 v19, v27, v106, v82
	v_fma_f32 v18, v28, v108, v82
	v_fma_f32 v17, v29, v110, v82
	v_fma_f32 v16, v30, v112, v82
	v_fmac_f32_e32 v82, v31, v114
	s_waitcnt vmcnt(0)
	v_fma_f32 v56, v0, v84, v83
	v_fma_f32 v31, v1, v86, v83
	v_fma_f32 v30, v2, v88, v83
	v_fma_f32 v29, v3, v90, v83
	v_fma_f32 v28, v4, v92, v83
	v_fma_f32 v27, v5, v94, v83
	v_fma_f32 v26, v6, v96, v83
	v_fma_f32 v25, v7, v98, v83
	v_fma_f32 v24, v8, v100, v83
	v_fma_f32 v9, v9, v102, v83
	v_fma_f32 v8, v10, v104, v83
	v_fma_f32 v7, v11, v106, v83
	v_fma_f32 v6, v12, v108, v83
	v_fma_f32 v5, v13, v110, v83
	v_fma_f32 v4, v14, v112, v83
	v_fmac_f32_e32 v83, v15, v114
	s_cbranch_scc0 .LBB0_496
	v_cndmask_b32_e64 v0, 0, 1, s[4:5]
	s_cmp_gt_u32 s10, 4
	v_cmp_ne_u32_e64 s[4:5], 1, v0
	s_cbranch_scc0 .LBB0_333
	v_mov_b32_e32 v0, s93
	ds_read_b64 v[0:1], v0
	v_and_b32_e32 v11, 64, v214
	v_xor_b32_e32 v10, 1, v214
	v_add_u32_e32 v13, 64, v11
	v_pk_mul_f32 v[2:3], v[78:79], v[78:79]
	s_waitcnt lgkmcnt(0)
	v_readfirstlane_b32 s80, v0
	v_readfirstlane_b32 s81, v1
	s_nop 4
	global_load_dword v1, v210, s[80:81] offset:1280
	global_load_dword v0, v210, s[80:81] offset:1408
	v_cmp_lt_i32_e32 vcc, v10, v13
	v_add_f32_e32 v2, v3, v2
	v_xor_b32_e32 v11, 4, v214
	v_cndmask_b32_e32 v3, v214, v10, vcc
	v_lshlrev_b32_e32 v14, 2, v3
	ds_bpermute_b32 v3, v14, v2
	v_xor_b32_e32 v10, 2, v214
	v_cmp_lt_i32_e32 vcc, v10, v13
	v_xor_b32_e32 v12, 8, v214
	v_xor_b32_e32 v15, 16, v214
	v_cndmask_b32_e32 v10, v214, v10, vcc
	v_lshlrev_b32_e32 v10, 2, v10
	s_waitcnt lgkmcnt(0)
	v_add_f32_e32 v2, v2, v3
	ds_bpermute_b32 v3, v10, v2
	v_cmp_lt_i32_e32 vcc, v11, v13
	s_mov_b64 s[80:81], -1
	s_waitcnt lgkmcnt(0)
	v_add_f32_e32 v2, v2, v3
	v_cndmask_b32_e32 v11, v214, v11, vcc
	v_lshlrev_b32_e32 v11, 2, v11
	ds_bpermute_b32 v3, v11, v2
	v_cmp_lt_i32_e32 vcc, v12, v13
	s_waitcnt lgkmcnt(0)
	v_add_f32_e32 v2, v2, v3
	v_cndmask_b32_e32 v12, v214, v12, vcc
	v_lshlrev_b32_e32 v12, 2, v12
	ds_bpermute_b32 v3, v12, v2
	v_cmp_lt_i32_e32 vcc, v15, v13
	s_waitcnt lgkmcnt(0)
	v_add_f32_e32 v2, v2, v3
	v_cndmask_b32_e32 v13, v214, v15, vcc
	v_lshlrev_b32_e32 v13, 2, v13
	ds_bpermute_b32 v3, v13, v2
	s_and_b64 vcc, exec, s[4:5]
	s_waitcnt lgkmcnt(0)
	v_add_f32_e32 v2, v2, v3
	v_fmamk_f32 v2, v2, 0x3c800000, v209
	v_rsq_f32_e32 v2, v2
	s_waitcnt vmcnt(0)
	v_pk_mul_f32 v[2:3], v[0:1], v[2:3] op_sel_hi:[1,0]
	s_nop 0
	v_pk_mul_f32 v[2:3], v[78:79], v[2:3]
	s_cbranch_vccnz .LBB0_270
	v_lshl_or_b32 v58, v164, 6, v156
	v_ashrrev_i32_e32 v59, 31, v58
	v_lshl_add_u64 v[58:59], v[58:59], 2, s[24:25]
	s_mov_b64 s[80:81], 0
	global_store_dword v[58:59], v3, off sc1
	global_store_dword v[58:59], v2, off offset:128 sc1

.LBB0_754:
	v_add_u32_e32 v82, s60, v93
	s_waitcnt lgkmcnt(0)
	v_or_b32_e32 v84, 8, v82
	s_add_i32 s59, s60, 0xffffe000
	s_lshr_b32 s59, s59, 12
	s_mulk_i32 s59, 0x1600
	s_addk_i32 s59, 0x1600
	s_cmp_gt_i32 s4, 63
	s_cselect_b32 s4, s59, 0
	s_lshl_b64 s[60:61], s[4:5], 2
	s_add_u32 s60, s10, s60
	s_addc_u32 s61, s11, s61
	v_or_b32_e32 v120, 1, v82
	v_or_b32_e32 v119, 2, v82
	v_or_b32_e32 v83, 3, v82
	s_add_i32 s3, s3, s33
	s_cmpk_gt_i32 s3, 0x15ff
	s_waitcnt vmcnt(0)
	v_or_b32_e32 v68, 9, v82
	v_or_b32_e32 v64, 16, v82
	v_mov_b32_e32 v71, v159
	v_or_b32_e32 v85, 10, v82
	v_or_b32_e32 v121, 18, v82
	v_or_b32_e32 v88, 17, v82
	v_or_b32_e32 v86, 24, v82
	v_ashrrev_i32_e32 v87, 31, v86
	v_lshl_add_u64 v[90:91], v[86:87], 2, s[6:7]
	v_or_b32_e32 v87, 11, v82
	v_add_co_u32_e32 v90, vcc, s75, v90
	s_nop 1
	v_addc_co_u32_e32 v91, vcc, 0, v91, vcc
	v_or_b32_e32 v90, 25, v82
	v_mov_b32_e32 v72, v160
	v_or_b32_e32 v66, s58, v92
	v_ashrrev_i32_e32 v67, 31, v66
	v_lshl_add_u64 v[66:67], v[66:67], 2, s[60:61]
	global_load_dword v122, v[66:67], off
	global_load_dword v65, v[66:67], off offset:128
	v_mov_b32_e32 v73, v161
	v_mov_b32_e32 v74, v162
	global_load_dword v126, v[66:67], off offset:256
	global_load_dword v66, v[66:67], off offset:384
	v_mov_b32_e32 v67, v156
	v_mov_b32_e32 v70, v157
	v_mov_b32_e32 v75, v163
	v_mov_b32_e32 v89, v164
	v_mov_b32_e32 v91, v165
	v_mov_b32_e32 v123, v166
	v_mov_b32_e32 v125, v167
	v_mov_b32_e32 v69, v168
	v_or_b32_e32 v124, 19, v82
	v_mov_b32_e32 v132, v158
	v_mov_b32_e32 v127, v169
	v_mov_b32_e32 v129, v170
	v_mov_b32_e32 v131, v171
	v_or_b32_e32 v128, 26, v82
	v_or_b32_e32 v130, 27, v82
	s_waitcnt vmcnt(3)
	v_fma_f32 v48, v48, v67, v122
	v_fma_f32 v49, v49, v70, v122
	s_waitcnt vmcnt(2)
	v_fma_f32 v32, v32, v67, v65
	v_fma_f32 v33, v33, v70, v65
	v_fma_f32 v34, v34, v132, v65
	v_fma_f32 v35, v35, v71, v65
	v_fma_f32 v36, v36, v72, v65
	v_fma_f32 v37, v37, v73, v65
	v_fma_f32 v38, v38, v74, v65
	v_fma_f32 v39, v39, v75, v65
	v_fma_f32 v40, v40, v89, v65
	v_fma_f32 v41, v41, v91, v65
	v_fma_f32 v42, v42, v123, v65
	v_fma_f32 v43, v43, v125, v65
	v_fma_f32 v44, v44, v69, v65
	v_fma_f32 v45, v45, v127, v65
	v_fma_f32 v46, v46, v129, v65
	v_fmac_f32_e32 v65, v47, v131
	s_waitcnt vmcnt(0)
	v_fma_f32 v47, v0, v67, v66
	v_mul_f32_e32 v0, 0xbfb8aa3b, v48
	v_fma_f32 v16, v16, v67, v126
	v_fma_f32 v67, v2, v132, v66
	v_exp_f32_e32 v2, v0
	v_fma_f32 v50, v50, v132, v122
	v_fma_f32 v51, v51, v71, v122
	v_fma_f32 v52, v52, v72, v122
	v_add_f32_e32 v2, 1.0, v2
	v_rcp_f32_e32 v2, v2
	v_fma_f32 v53, v53, v73, v122
	v_fma_f32 v54, v54, v74, v122
	v_fma_f32 v55, v55, v75, v122
	v_fma_f32 v56, v56, v89, v122
	v_fma_f32 v57, v57, v91, v122
	v_fma_f32 v58, v58, v123, v122
	v_fma_f32 v59, v59, v125, v122
	v_fma_f32 v60, v60, v69, v122
	v_fma_f32 v61, v61, v127, v122
	v_fma_f32 v62, v62, v129, v122
	v_fmac_f32_e32 v122, v63, v131
	v_fma_f32 v17, v17, v70, v126
	v_fma_f32 v63, v1, v70, v66
	v_fma_f32 v70, v3, v71, v66
	v_mul_f32_e32 v3, 0xbfb8aa3b, v49
	v_exp_f32_e32 v3, v3
	v_mul_f32_e32 v2, v48, v2
	v_mul_f32_e32 v2, v16, v2
	v_fma_f32 v19, v19, v71, v126
	v_fma_f32 v71, v4, v72, v66
	v_cvt_pk_bf16_f32 v4, v2, s0
	v_add_f32_e32 v2, 1.0, v3
	v_fma_f32 v20, v20, v72, v126
	v_fma_f32 v72, v5, v73, v66
	v_lshl_or_b32 v0, s76, 6, v92
	v_rcp_f32_e32 v5, v2
	v_ashrrev_i32_e32 v1, 31, v0
	v_lshl_add_u64 v[0:1], v[0:1], 1, s[8:9]
	v_mad_i64_i32 v[2:3], s[58:59], v82, s68, v[0:1]
	global_store_short v[2:3], v4, off sc1
	v_mul_f32_e32 v4, v49, v5
	v_mul_f32_e32 v5, 0xbfb8aa3b, v50
	v_fma_f32 v21, v21, v73, v126
	v_fma_f32 v73, v6, v74, v66
	v_exp_f32_e32 v6, v5
	v_mul_f32_e32 v4, v17, v4
	v_fma_f32 v22, v22, v74, v126
	v_fma_f32 v74, v7, v75, v66
	v_add_f32_e32 v6, 1.0, v6
	v_cvt_pk_bf16_f32 v7, v4, s0
	v_mad_i64_i32 v[4:5], s[58:59], v120, s68, v[0:1]
	v_rcp_f32_e32 v6, v6
	global_store_short v[4:5], v7, off sc1
	v_mul_f32_e32 v7, 0xbfb8aa3b, v51
	v_exp_f32_e32 v7, v7
	v_fma_f32 v18, v18, v132, v126
	v_mul_f32_e32 v6, v50, v6
	v_mul_f32_e32 v6, v18, v6
	v_fma_f32 v23, v23, v75, v126
	v_fma_f32 v75, v8, v89, v66
	v_cvt_pk_bf16_f32 v8, v6, s0
	v_add_f32_e32 v6, 1.0, v7
	v_fma_f32 v24, v24, v89, v126
	v_fma_f32 v89, v9, v91, v66
	v_rcp_f32_e32 v9, v6
	v_mad_i64_i32 v[6:7], s[58:59], v119, s68, v[0:1]
	global_store_short v[6:7], v8, off sc1
	v_mul_f32_e32 v8, v51, v9
	v_mul_f32_e32 v9, 0xbfb8aa3b, v52
	v_fma_f32 v25, v25, v91, v126
	v_fma_f32 v91, v10, v123, v66
	v_exp_f32_e32 v10, v9
	v_mul_f32_e32 v8, v19, v8
	v_fma_f32 v26, v26, v123, v126
	v_fma_f32 v123, v11, v125, v66
	v_add_f32_e32 v10, 1.0, v10
	v_cvt_pk_bf16_f32 v11, v8, s0
	v_mad_i64_i32 v[8:9], s[58:59], v83, s68, v[0:1]
	v_rcp_f32_e32 v10, v10
	global_store_short v[8:9], v11, off sc1
	v_mul_f32_e32 v11, 0xbfb8aa3b, v53
	v_exp_f32_e32 v11, v11
	v_mul_f32_e32 v10, v52, v10
	v_mul_f32_e32 v10, v20, v10
	v_fma_f32 v28, v28, v69, v126
	v_fma_f32 v69, v12, v69, v66
	v_cvt_pk_bf16_f32 v12, v10, s0
	v_add_f32_e32 v10, 1.0, v11
	v_fma_f32 v27, v27, v125, v126
	v_fma_f32 v125, v13, v127, v66
	v_rcp_f32_e32 v13, v10
	v_mad_i64_i32 v[10:11], s[58:59], v84, s68, v[0:1]
	global_store_short v[10:11], v12, off sc1
	v_mul_f32_e32 v12, v53, v13
	v_mul_f32_e32 v13, 0xbfb8aa3b, v54
	v_fma_f32 v29, v29, v127, v126
	v_fma_f32 v127, v14, v129, v66
	v_exp_f32_e32 v14, v13
	v_mul_f32_e32 v12, v21, v12
	v_fmac_f32_e32 v66, v15, v131
	v_cvt_pk_bf16_f32 v15, v12, s0
	v_add_f32_e32 v14, 1.0, v14
	v_mad_i64_i32 v[12:13], s[58:59], v68, s68, v[0:1]
	v_rcp_f32_e32 v14, v14
	global_store_short v[12:13], v15, off sc1
	v_mul_f32_e32 v15, 0xbfb8aa3b, v55
	v_exp_f32_e32 v15, v15
	v_mul_f32_e32 v14, v54, v14
	v_mul_f32_e32 v14, v22, v14
	v_cvt_pk_bf16_f32 v16, v14, s0
	v_add_f32_e32 v14, 1.0, v15
	v_rcp_f32_e32 v17, v14
	v_mad_i64_i32 v[14:15], s[58:59], v85, s68, v[0:1]
	global_store_short v[14:15], v16, off sc1
	v_mul_f32_e32 v16, v55, v17
	v_mul_f32_e32 v17, 0xbfb8aa3b, v56
	v_exp_f32_e32 v18, v17
	v_mul_f32_e32 v16, v23, v16
	v_cvt_pk_bf16_f32 v19, v16, s0
	v_mad_i64_i32 v[16:17], s[58:59], v87, s68, v[0:1]
	v_add_f32_e32 v18, 1.0, v18
	v_rcp_f32_e32 v18, v18
	global_store_short v[16:17], v19, off sc1
	v_mul_f32_e32 v19, 0xbfb8aa3b, v57
	v_exp_f32_e32 v19, v19
	v_mul_f32_e32 v18, v56, v18
	v_mul_f32_e32 v18, v24, v18
	v_cvt_pk_bf16_f32 v20, v18, s0
	v_add_f32_e32 v18, 1.0, v19
	v_rcp_f32_e32 v21, v18
	v_mad_i64_i32 v[18:19], s[58:59], v64, s68, v[0:1]
	global_store_short v[18:19], v20, off sc1
	v_mul_f32_e32 v20, v57, v21
	v_mul_f32_e32 v21, 0xbfb8aa3b, v58
	v_exp_f32_e32 v22, v21
	v_mul_f32_e32 v20, v25, v20
	v_cvt_pk_bf16_f32 v23, v20, s0
	v_mad_i64_i32 v[20:21], s[58:59], v88, s68, v[0:1]
	v_add_f32_e32 v22, 1.0, v22
	v_rcp_f32_e32 v22, v22
	global_store_short v[20:21], v23, off sc1
	v_mul_f32_e32 v23, 0xbfb8aa3b, v59
	v_exp_f32_e32 v23, v23
	v_mul_f32_e32 v22, v58, v22
	v_mul_f32_e32 v22, v26, v22
	v_cvt_pk_bf16_f32 v24, v22, s0
	v_add_f32_e32 v22, 1.0, v23
	v_rcp_f32_e32 v25, v22
	v_mad_i64_i32 v[22:23], s[58:59], v121, s68, v[0:1]
	global_store_short v[22:23], v24, off sc1
	v_mul_f32_e32 v24, v59, v25
	v_mul_f32_e32 v25, 0xbfb8aa3b, v60
	v_exp_f32_e32 v26, v25
	v_mul_f32_e32 v24, v27, v24
	v_cvt_pk_bf16_f32 v27, v24, s0
	v_mad_i64_i32 v[24:25], s[58:59], v124, s68, v[0:1]
	v_add_f32_e32 v26, 1.0, v26
	v_rcp_f32_e32 v26, v26
	global_store_short v[24:25], v27, off sc1
	v_mul_f32_e32 v27, 0xbfb8aa3b, v61
	v_exp_f32_e32 v27, v27
	v_mul_f32_e32 v26, v60, v26
	v_mul_f32_e32 v26, v28, v26
	v_cvt_pk_bf16_f32 v28, v26, s0
	v_add_f32_e32 v26, 1.0, v27
	v_fma_f32 v30, v30, v129, v126
	v_fmac_f32_e32 v126, v31, v131
	v_rcp_f32_e32 v31, v26
	v_mad_i64_i32 v[26:27], s[58:59], v86, s68, v[0:1]
	global_store_short v[26:27], v28, off sc1
	v_mul_f32_e32 v28, v61, v31
	v_mul_f32_e32 v28, v29, v28
	v_mul_f32_e32 v29, 0xbfb8aa3b, v62
	v_exp_f32_e32 v31, v29
	v_cvt_pk_bf16_f32 v48, v28, s0
	v_mad_i64_i32 v[28:29], s[58:59], v90, s68, v[0:1]
	v_add_f32_e32 v31, 1.0, v31
	v_rcp_f32_e32 v31, v31
	global_store_short v[28:29], v48, off sc1
	v_mul_f32_e32 v48, 0xbfb8aa3b, v122
	v_exp_f32_e32 v48, v48
	v_mul_f32_e32 v31, v62, v31
	v_mul_f32_e32 v30, v30, v31
	v_cvt_pk_bf16_f32 v49, v30, s0
	v_add_f32_e32 v30, 1.0, v48
	v_rcp_f32_e32 v48, v30
	v_mad_i64_i32 v[30:31], s[58:59], v128, s68, v[0:1]
	global_store_short v[30:31], v49, off sc1
	v_mul_f32_e32 v49, 0xbfb8aa3b, v32
	v_exp_f32_e32 v49, v49
	v_mul_f32_e32 v48, v122, v48
	v_mul_f32_e32 v48, v126, v48
	v_cvt_pk_bf16_f32 v48, v48, s0
	v_mad_i64_i32 v[0:1], s[58:59], v130, s68, v[0:1]
	v_add_f32_e32 v49, 1.0, v49
	v_rcp_f32_e32 v49, v49
	global_store_short v[0:1], v48, off sc1
	v_mul_f32_e32 v48, 0xbfb8aa3b, v33
	v_exp_f32_e32 v48, v48
	v_mul_f32_e32 v32, v32, v49
	v_mul_f32_e32 v32, v47, v32
	v_cvt_pk_bf16_f32 v32, v32, s0
	v_add_f32_e32 v47, 1.0, v48
	v_rcp_f32_e32 v47, v47
	global_store_short v[2:3], v32, off offset:64 sc1
	v_mul_f32_e32 v2, 0xbfb8aa3b, v34
	v_exp_f32_e32 v2, v2
	v_mul_f32_e32 v3, v33, v47
	v_mul_f32_e32 v3, v63, v3
	v_cvt_pk_bf16_f32 v3, v3, s0
	global_store_short v[4:5], v3, off offset:64 sc1
	v_mul_f32_e32 v3, 0xbfb8aa3b, v35
	v_exp_f32_e32 v3, v3
	v_add_f32_e32 v2, 1.0, v2
	v_rcp_f32_e32 v2, v2
	v_mul_f32_e32 v4, 0xbfb8aa3b, v46
	v_add_f32_e32 v3, 1.0, v3
	v_rcp_f32_e32 v3, v3
	v_mul_f32_e32 v2, v34, v2
	v_mul_f32_e32 v2, v67, v2
	v_cvt_pk_bf16_f32 v2, v2, s0
	global_store_short v[6:7], v2, off offset:64 sc1
	v_mul_f32_e32 v2, 0xbfb8aa3b, v36
	v_mul_f32_e32 v3, v35, v3
	v_exp_f32_e32 v2, v2
	v_mul_f32_e32 v3, v70, v3
	v_cvt_pk_bf16_f32 v3, v3, s0
	global_store_short v[8:9], v3, off offset:64 sc1
	v_mul_f32_e32 v3, 0xbfb8aa3b, v37
	v_exp_f32_e32 v3, v3
	v_add_f32_e32 v2, 1.0, v2
	v_rcp_f32_e32 v2, v2
	v_exp_f32_e32 v4, v4
	v_add_f32_e32 v3, 1.0, v3
	v_rcp_f32_e32 v3, v3
	v_mul_f32_e32 v2, v36, v2
	v_mul_f32_e32 v2, v71, v2
	v_cvt_pk_bf16_f32 v2, v2, s0
	global_store_short v[10:11], v2, off offset:64 sc1
	v_mul_f32_e32 v2, 0xbfb8aa3b, v38
	v_mul_f32_e32 v3, v37, v3
	v_exp_f32_e32 v2, v2
	v_mul_f32_e32 v3, v72, v3
	v_cvt_pk_bf16_f32 v3, v3, s0
	global_store_short v[12:13], v3, off offset:64 sc1
	v_mul_f32_e32 v3, 0xbfb8aa3b, v39
	v_exp_f32_e32 v3, v3
	v_add_f32_e32 v2, 1.0, v2
	v_rcp_f32_e32 v2, v2
	v_add_f32_e32 v3, 1.0, v3
	v_rcp_f32_e32 v3, v3
	v_mul_f32_e32 v2, v38, v2
	v_mul_f32_e32 v2, v73, v2
	v_cvt_pk_bf16_f32 v2, v2, s0
	global_store_short v[14:15], v2, off offset:64 sc1
	v_mul_f32_e32 v2, 0xbfb8aa3b, v40
	v_mul_f32_e32 v3, v39, v3
	v_exp_f32_e32 v2, v2
	v_mul_f32_e32 v3, v74, v3
	v_cvt_pk_bf16_f32 v3, v3, s0
	global_store_short v[16:17], v3, off offset:64 sc1
	v_mul_f32_e32 v3, 0xbfb8aa3b, v41
	v_exp_f32_e32 v3, v3
	v_add_f32_e32 v2, 1.0, v2
	v_rcp_f32_e32 v2, v2
	v_add_f32_e32 v3, 1.0, v3
	v_rcp_f32_e32 v3, v3
	v_mul_f32_e32 v2, v40, v2
	v_mul_f32_e32 v2, v75, v2
	v_cvt_pk_bf16_f32 v2, v2, s0
	global_store_short v[18:19], v2, off offset:64 sc1
	v_mul_f32_e32 v2, 0xbfb8aa3b, v42
	v_mul_f32_e32 v3, v41, v3
	v_exp_f32_e32 v2, v2
	v_mul_f32_e32 v3, v89, v3
	v_cvt_pk_bf16_f32 v3, v3, s0
	global_store_short v[20:21], v3, off offset:64 sc1
	v_mul_f32_e32 v3, 0xbfb8aa3b, v43
	v_exp_f32_e32 v3, v3
	v_add_f32_e32 v2, 1.0, v2
	v_rcp_f32_e32 v2, v2
	v_add_f32_e32 v3, 1.0, v3
	v_rcp_f32_e32 v3, v3
	v_mul_f32_e32 v2, v42, v2
	v_mul_f32_e32 v2, v91, v2
	v_cvt_pk_bf16_f32 v2, v2, s0
	global_store_short v[22:23], v2, off offset:64 sc1
	v_mul_f32_e32 v2, 0xbfb8aa3b, v44
	v_mul_f32_e32 v3, v43, v3
	v_exp_f32_e32 v2, v2
	v_mul_f32_e32 v3, v123, v3
	v_cvt_pk_bf16_f32 v3, v3, s0
	global_store_short v[24:25], v3, off offset:64 sc1
	v_mul_f32_e32 v3, 0xbfb8aa3b, v45
	v_exp_f32_e32 v3, v3
	v_add_f32_e32 v2, 1.0, v2
	v_rcp_f32_e32 v2, v2
	v_add_f32_e32 v3, 1.0, v3
	v_rcp_f32_e32 v3, v3
	v_mul_f32_e32 v2, v44, v2
	v_mul_f32_e32 v2, v69, v2
	v_cvt_pk_bf16_f32 v2, v2, s0
	global_store_short v[26:27], v2, off offset:64 sc1
	v_mul_f32_e32 v2, v45, v3
	v_add_f32_e32 v3, 1.0, v4
	v_mul_f32_e32 v4, 0xbfb8aa3b, v65
	v_rcp_f32_e32 v3, v3
	v_exp_f32_e32 v4, v4
	v_mul_f32_e32 v2, v125, v2
	v_cvt_pk_bf16_f32 v2, v2, s0
	global_store_short v[28:29], v2, off offset:64 sc1
	v_mul_f32_e32 v2, v46, v3
	v_add_f32_e32 v3, 1.0, v4
	v_rcp_f32_e32 v3, v3
	v_mul_f32_e32 v2, v127, v2
	v_cvt_pk_bf16_f32 v2, v2, s0
	global_store_short v[30:31], v2, off offset:64 sc1
	v_mul_f32_e32 v2, v65, v3
	v_mul_f32_e32 v2, v66, v2
	v_cvt_pk_bf16_f32 v2, v2, s0
	global_store_short v[0:1], v2, off offset:64 sc1
	s_cbranch_scc1 .LBB0_759

.Lgk_pfhead_p7:
	v_and_b32_e32 v152, 31, v199
	v_bfe_u32 v153, v199, 5, 1
	v_lshlrev_b32_e32 v154, 2, v153
	v_sub_u32_e32 v152, v152, v154
	v_add_u32_e32 v154, s60, v93
	v_add_lshl_u32 v152, v152, v154, 2
	v_lshlrev_b32_e32 v153, 4, v153
	global_load_dword v144, v152, s[6:7]
	v_add_u32_e32 v154, 0x10000, v152
	global_load_dword v145, v154, s[6:7]
	v_add_u32_e32 v154, 0x20000, v152
	global_load_dword v146, v154, s[6:7]
	v_add_u32_e32 v154, 0x30000, v152
	global_load_dword v147, v154, s[6:7]
	v_add_u32_e32 v154, 0x40000, v152
	global_load_dword v148, v154, s[6:7]
	v_add_u32_e32 v154, 0x50000, v152
	global_load_dword v149, v154, s[6:7]
	v_add_u32_e32 v154, 0x60000, v152
	global_load_dword v150, v154, s[6:7]
	v_add_u32_e32 v154, 0x70000, v152
	global_load_dword v151, v154, s[6:7]
	v_mov_b32_e32 v48, 0
	v_mov_b32_e32 v49, 0
	v_mov_b32_e32 v50, 0
	v_mov_b32_e32 v51, 0
	v_mov_b32_e32 v52, 0
	v_mov_b32_e32 v53, 0
	v_mov_b32_e32 v54, 0
	v_mov_b32_e32 v55, 0
	v_mov_b32_e32 v56, 0
	v_mov_b32_e32 v57, 0
	v_mov_b32_e32 v58, 0
	v_mov_b32_e32 v59, 0
	v_mov_b32_e32 v60, 0
	v_mov_b32_e32 v61, 0
	v_mov_b32_e32 v62, 0
	v_mov_b32_e32 v63, 0
	v_mov_b32_e32 v32, 0
	v_mov_b32_e32 v33, 0
	v_mov_b32_e32 v34, 0
	v_mov_b32_e32 v35, 0
	v_mov_b32_e32 v36, 0
	v_mov_b32_e32 v37, 0
	v_mov_b32_e32 v38, 0
	v_mov_b32_e32 v39, 0
	v_mov_b32_e32 v40, 0
	v_mov_b32_e32 v41, 0
	v_mov_b32_e32 v42, 0
	v_mov_b32_e32 v43, 0
	v_mov_b32_e32 v44, 0
	v_mov_b32_e32 v45, 0
	v_mov_b32_e32 v46, 0
	v_mov_b32_e32 v47, 0
	v_mov_b32_e32 v16, 0
	v_mov_b32_e32 v17, 0
	v_mov_b32_e32 v18, 0
	v_mov_b32_e32 v19, 0
	v_mov_b32_e32 v20, 0
	v_mov_b32_e32 v21, 0
	v_mov_b32_e32 v22, 0
	v_mov_b32_e32 v23, 0
	v_mov_b32_e32 v24, 0
	v_mov_b32_e32 v25, 0
	v_mov_b32_e32 v26, 0
	v_mov_b32_e32 v27, 0
	v_mov_b32_e32 v28, 0
	v_mov_b32_e32 v29, 0
	v_mov_b32_e32 v30, 0
	v_mov_b32_e32 v31, 0
	v_mov_b32_e32 v0, 0
	v_mov_b32_e32 v1, 0
	v_mov_b32_e32 v2, 0
	v_mov_b32_e32 v3, 0
	v_mov_b32_e32 v4, 0
	v_mov_b32_e32 v5, 0
	v_mov_b32_e32 v6, 0
	v_mov_b32_e32 v7, 0
	v_mov_b32_e32 v8, 0
	v_mov_b32_e32 v9, 0
	v_mov_b32_e32 v10, 0
	v_mov_b32_e32 v11, 0
	v_mov_b32_e32 v12, 0
	v_mov_b32_e32 v13, 0
	v_mov_b32_e32 v14, 0
	v_mov_b32_e32 v15, 0
	s_mov_b32 s37, 7

.Lmap_done_0_pf_p7:
	s_lshl_b32 s44, s41, 7
	s_lshl_b32 s42, s50, 7
	s_ashr_i32 s45, s44, 31
	s_ashr_i32 s43, s42, 31
	s_lshl_b64 s[46:47], s[44:45], 11
	s_lshl_b64 s[48:49], s[42:43], 11
	s_lshl_b32 s38, s44, 11
	s_add_u32 s18, s14, s38
	s_addc_u32 s19, s15, 0
	s_add_u32 s18, s18, 0x679f000
	s_addc_u32 s19, s19, 0
	s_add_u32 s20, s18, 0x10000
	s_addc_u32 s21, s19, 0
	s_add_u32 s22, s20, 0x10000
	s_addc_u32 s23, s21, 0
	s_add_u32 s24, s22, 0x10000
	s_addc_u32 s25, s23, 0
	s_lshl_b32 s38, s42, 11
	s_add_u32 s26, s14, s38
	s_addc_u32 s27, s15, 0
	s_add_u32 s26, s26, 0x19a0000
	s_addc_u32 s27, s27, 0
	s_add_u32 s28, s26, 0x10000
	s_addc_u32 s29, s27, 0
	s_add_u32 s30, s28, 0x10000
	s_addc_u32 s31, s29, 0
	s_add_u32 s34, s30, 0x10000
	s_addc_u32 s35, s31, 0
	v_mov_b32_e32 v254, v76
	s_mov_b32 s39, 1
	s_waitcnt vmcnt(8)
	s_barrier
	ds_read_b128 v[64:67], v110
	ds_read_b128 v[68:71], v111 offset:16384
	ds_read_b128 v[72:75], v111 offset:20480
	ds_read_b128 v[82:85], v111 offset:24576
	ds_read_b128 v[86:89], v111 offset:28672
	ds_read_b128 v[120:123], v112
	ds_read_b128 v[124:127], v113 offset:16384
	ds_read_b128 v[128:131], v113 offset:20480
	ds_read_b128 v[132:135], v113 offset:24576
	ds_read_b128 v[136:139], v113 offset:28672
	ds_read_b128 v[140:143], v114
	ds_read_b128 v[218:221], v115 offset:16384
	ds_read_b128 v[222:225], v115 offset:20480
	ds_read_b128 v[226:229], v115 offset:24576
	ds_read_b128 v[230:233], v115 offset:28672
	ds_read_b128 v[234:237], v116
	ds_read_b128 v[238:241], v117 offset:16384
	ds_read_b128 v[242:245], v117 offset:20480
	ds_read_b128 v[246:249], v117 offset:24576
	ds_read_b128 v[250:253], v117 offset:28672
	s_waitcnt lgkmcnt(0)
	s_barrier
	s_mov_b32 m0, s36
	s_setprio 1
	v_mfma_f32_32x32x16_bf16 v[48:63], v[64:67], v[68:71], v[48:63]
	v_mfma_f32_32x32x16_bf16 v[32:47], v[64:67], v[72:75], v[32:47]
	global_load_lds_dwordx4 v254, s[18:19]
	s_add_u32 m0, m0, 0x1000
	v_mfma_f32_32x32x16_bf16 v[16:31], v[64:67], v[82:85], v[16:31]
	v_mfma_f32_32x32x16_bf16 v[0:15], v[64:67], v[86:89], v[0:15]
	global_load_lds_dwordx4 v254, s[20:21]
	s_add_u32 m0, m0, 0x1000
	v_mfma_f32_32x32x16_bf16 v[48:63], v[120:123], v[124:127], v[48:63]
	v_mfma_f32_32x32x16_bf16 v[32:47], v[120:123], v[128:131], v[32:47]
	global_load_lds_dwordx4 v254, s[22:23]
	s_add_u32 m0, m0, 0x1000
	v_mfma_f32_32x32x16_bf16 v[16:31], v[120:123], v[132:135], v[16:31]
	v_mfma_f32_32x32x16_bf16 v[0:15], v[120:123], v[136:139], v[0:15]
	global_load_lds_dwordx4 v254, s[24:25]
	s_add_u32 m0, m0, 0x1000
	v_mfma_f32_32x32x16_bf16 v[48:63], v[140:143], v[218:221], v[48:63]
	v_mfma_f32_32x32x16_bf16 v[32:47], v[140:143], v[222:225], v[32:47]
	global_load_lds_dwordx4 v254, s[26:27]
	s_add_u32 m0, m0, 0x1000
	v_mfma_f32_32x32x16_bf16 v[16:31], v[140:143], v[226:229], v[16:31]
	v_mfma_f32_32x32x16_bf16 v[0:15], v[140:143], v[230:233], v[0:15]
	global_load_lds_dwordx4 v254, s[28:29]
	s_add_u32 m0, m0, 0x1000
	v_mfma_f32_32x32x16_bf16 v[48:63], v[234:237], v[238:241], v[48:63]
	v_mfma_f32_32x32x16_bf16 v[32:47], v[234:237], v[242:245], v[32:47]
	global_load_lds_dwordx4 v254, s[30:31]
	s_add_u32 m0, m0, 0x1000
	v_mfma_f32_32x32x16_bf16 v[16:31], v[234:237], v[246:249], v[16:31]
	v_mfma_f32_32x32x16_bf16 v[0:15], v[234:237], v[250:253], v[0:15]
	global_load_lds_dwordx4 v254, s[34:35]
	s_setprio 0
	v_add_u32_e32 v254, 0x80, v254
	s_waitcnt vmcnt(8)
	s_barrier
	ds_read_b128 v[64:67], v110 offset:32768
	ds_read_b128 v[68:71], v111 offset:49152
	ds_read_b128 v[72:75], v111 offset:53248
	ds_read_b128 v[82:85], v111 offset:57344
	ds_read_b128 v[86:89], v111 offset:61440
	ds_read_b128 v[120:123], v112 offset:32768
	ds_read_b128 v[124:127], v113 offset:49152
	ds_read_b128 v[128:131], v113 offset:53248
	ds_read_b128 v[132:135], v113 offset:57344
	ds_read_b128 v[136:139], v113 offset:61440
	ds_read_b128 v[140:143], v114 offset:32768
	ds_read_b128 v[218:221], v115 offset:49152
	ds_read_b128 v[222:225], v115 offset:53248
	ds_read_b128 v[226:229], v115 offset:57344
	ds_read_b128 v[230:233], v115 offset:61440
	ds_read_b128 v[234:237], v116 offset:32768
	ds_read_b128 v[238:241], v117 offset:49152
	ds_read_b128 v[242:245], v117 offset:53248
	ds_read_b128 v[246:249], v117 offset:57344
	ds_read_b128 v[250:253], v117 offset:61440
	s_waitcnt lgkmcnt(0)
	s_barrier
	s_add_u32 m0, s36, 0x8000
	s_setprio 1
	v_mfma_f32_32x32x16_bf16 v[48:63], v[64:67], v[68:71], v[48:63]
	v_add_f32_e32 v144, v144, v145
	v_add_f32_e32 v146, v146, v147
	v_mfma_f32_32x32x16_bf16 v[32:47], v[64:67], v[72:75], v[32:47]
	v_add_f32_e32 v148, v148, v149
	v_add_f32_e32 v150, v150, v151
	global_load_lds_dwordx4 v254, s[18:19]
	s_add_u32 m0, m0, 0x1000
	v_mfma_f32_32x32x16_bf16 v[16:31], v[64:67], v[82:85], v[16:31]
	v_add_f32_e32 v144, v144, v146
	v_add_f32_e32 v148, v148, v150
	v_mfma_f32_32x32x16_bf16 v[0:15], v[64:67], v[86:89], v[0:15]
	v_add_f32_e32 v144, v144, v148
	v_fmamk_f32 v144, v144, 0x3a800000, v118
	global_load_lds_dwordx4 v254, s[20:21]
	s_add_u32 m0, m0, 0x1000
	v_mfma_f32_32x32x16_bf16 v[48:63], v[120:123], v[124:127], v[48:63]
	v_rsq_f32_e32 v144, v144
	s_nop 1
	v_mfma_f32_32x32x16_bf16 v[32:47], v[120:123], v[128:131], v[32:47]
	ds_bpermute_b32 v156, v153, v144
	ds_bpermute_b32 v157, v153, v144 offset:4
	global_load_lds_dwordx4 v254, s[22:23]
	s_add_u32 m0, m0, 0x1000
	v_mfma_f32_32x32x16_bf16 v[16:31], v[120:123], v[132:135], v[16:31]
	ds_bpermute_b32 v158, v153, v144 offset:8
	ds_bpermute_b32 v159, v153, v144 offset:12
	v_mfma_f32_32x32x16_bf16 v[0:15], v[120:123], v[136:139], v[0:15]
	ds_bpermute_b32 v160, v153, v144 offset:32
	ds_bpermute_b32 v161, v153, v144 offset:36
	global_load_lds_dwordx4 v254, s[24:25]
	s_add_u32 m0, m0, 0x1000
	v_mfma_f32_32x32x16_bf16 v[48:63], v[140:143], v[218:221], v[48:63]
	ds_bpermute_b32 v162, v153, v144 offset:40
	ds_bpermute_b32 v163, v153, v144 offset:44
	v_mfma_f32_32x32x16_bf16 v[32:47], v[140:143], v[222:225], v[32:47]
	ds_bpermute_b32 v164, v153, v144 offset:64
	ds_bpermute_b32 v165, v153, v144 offset:68
	global_load_lds_dwordx4 v254, s[26:27]
	s_add_u32 m0, m0, 0x1000
	v_mfma_f32_32x32x16_bf16 v[16:31], v[140:143], v[226:229], v[16:31]
	ds_bpermute_b32 v166, v153, v144 offset:72
	ds_bpermute_b32 v167, v153, v144 offset:76
	v_mfma_f32_32x32x16_bf16 v[0:15], v[140:143], v[230:233], v[0:15]
	ds_bpermute_b32 v168, v153, v144 offset:96
	ds_bpermute_b32 v169, v153, v144 offset:100
	global_load_lds_dwordx4 v254, s[28:29]
	s_add_u32 m0, m0, 0x1000
	v_mfma_f32_32x32x16_bf16 v[48:63], v[234:237], v[238:241], v[48:63]
	ds_bpermute_b32 v170, v153, v144 offset:104
	ds_bpermute_b32 v171, v153, v144 offset:108
	v_mfma_f32_32x32x16_bf16 v[32:47], v[234:237], v[242:245], v[32:47]
	global_load_lds_dwordx4 v254, s[30:31]
	s_add_u32 m0, m0, 0x1000
	v_mfma_f32_32x32x16_bf16 v[16:31], v[234:237], v[246:249], v[16:31]
	v_mfma_f32_32x32x16_bf16 v[0:15], v[234:237], v[250:253], v[0:15]
	global_load_lds_dwordx4 v254, s[34:35]
	s_setprio 0
	v_add_u32_e32 v254, 0x80, v254
	s_branch .LBB0_754
.Lgk_tailplain_p7:
	s_mov_b32 s39, 0
	s_waitcnt vmcnt(8)
	s_barrier
	ds_read_b128 v[64:67], v110
	ds_read_b128 v[68:71], v111 offset:16384
	ds_read_b128 v[72:75], v111 offset:20480
	ds_read_b128 v[82:85], v111 offset:24576
	ds_read_b128 v[86:89], v111 offset:28672
	ds_read_b128 v[120:123], v112
	ds_read_b128 v[124:127], v113 offset:16384
	ds_read_b128 v[128:131], v113 offset:20480
	ds_read_b128 v[132:135], v113 offset:24576
	ds_read_b128 v[136:139], v113 offset:28672
	ds_read_b128 v[140:143], v114
	ds_read_b128 v[218:221], v115 offset:16384
	ds_read_b128 v[222:225], v115 offset:20480
	ds_read_b128 v[226:229], v115 offset:24576
	ds_read_b128 v[230:233], v115 offset:28672
	ds_read_b128 v[234:237], v116
	ds_read_b128 v[238:241], v117 offset:16384
	ds_read_b128 v[242:245], v117 offset:20480
	ds_read_b128 v[246:249], v117 offset:24576
	ds_read_b128 v[250:253], v117 offset:28672
	s_waitcnt lgkmcnt(0)
	s_barrier
	s_setprio 1
	v_mfma_f32_32x32x16_bf16 v[48:63], v[64:67], v[68:71], v[48:63]
	v_mfma_f32_32x32x16_bf16 v[32:47], v[64:67], v[72:75], v[32:47]
	v_mfma_f32_32x32x16_bf16 v[16:31], v[64:67], v[82:85], v[16:31]
	v_mfma_f32_32x32x16_bf16 v[0:15], v[64:67], v[86:89], v[0:15]
	v_mfma_f32_32x32x16_bf16 v[48:63], v[120:123], v[124:127], v[48:63]
	v_mfma_f32_32x32x16_bf16 v[32:47], v[120:123], v[128:131], v[32:47]
	v_mfma_f32_32x32x16_bf16 v[16:31], v[120:123], v[132:135], v[16:31]
	v_mfma_f32_32x32x16_bf16 v[0:15], v[120:123], v[136:139], v[0:15]
	v_mfma_f32_32x32x16_bf16 v[48:63], v[140:143], v[218:221], v[48:63]
	v_mfma_f32_32x32x16_bf16 v[32:47], v[140:143], v[222:225], v[32:47]
	v_mfma_f32_32x32x16_bf16 v[16:31], v[140:143], v[226:229], v[16:31]
	v_mfma_f32_32x32x16_bf16 v[0:15], v[140:143], v[230:233], v[0:15]
	v_mfma_f32_32x32x16_bf16 v[48:63], v[234:237], v[238:241], v[48:63]
	v_mfma_f32_32x32x16_bf16 v[32:47], v[234:237], v[242:245], v[32:47]
	v_mfma_f32_32x32x16_bf16 v[16:31], v[234:237], v[246:249], v[16:31]
	v_mfma_f32_32x32x16_bf16 v[0:15], v[234:237], v[250:253], v[0:15]
	s_setprio 0
	s_waitcnt vmcnt(0)
	s_barrier
	ds_read_b128 v[64:67], v110 offset:32768
	ds_read_b128 v[68:71], v111 offset:49152
	ds_read_b128 v[72:75], v111 offset:53248
	ds_read_b128 v[82:85], v111 offset:57344
	ds_read_b128 v[86:89], v111 offset:61440
	ds_read_b128 v[120:123], v112 offset:32768
	ds_read_b128 v[124:127], v113 offset:49152
	ds_read_b128 v[128:131], v113 offset:53248
	ds_read_b128 v[132:135], v113 offset:57344
	ds_read_b128 v[136:139], v113 offset:61440
	ds_read_b128 v[140:143], v114 offset:32768
	ds_read_b128 v[218:221], v115 offset:49152
	ds_read_b128 v[222:225], v115 offset:53248
	ds_read_b128 v[226:229], v115 offset:57344
	ds_read_b128 v[230:233], v115 offset:61440
	ds_read_b128 v[234:237], v116 offset:32768
	ds_read_b128 v[238:241], v117 offset:49152
	ds_read_b128 v[242:245], v117 offset:53248
	ds_read_b128 v[246:249], v117 offset:57344
	ds_read_b128 v[250:253], v117 offset:61440
	s_waitcnt lgkmcnt(0)
	s_barrier
	s_setprio 1
	v_mfma_f32_32x32x16_bf16 v[48:63], v[64:67], v[68:71], v[48:63]
	v_add_f32_e32 v144, v144, v145
	v_add_f32_e32 v146, v146, v147
	v_mfma_f32_32x32x16_bf16 v[32:47], v[64:67], v[72:75], v[32:47]
	v_add_f32_e32 v148, v148, v149
	v_add_f32_e32 v150, v150, v151
	v_mfma_f32_32x32x16_bf16 v[16:31], v[64:67], v[82:85], v[16:31]
	v_add_f32_e32 v144, v144, v146
	v_add_f32_e32 v148, v148, v150
	v_mfma_f32_32x32x16_bf16 v[0:15], v[64:67], v[86:89], v[0:15]
	v_add_f32_e32 v144, v144, v148
	v_fmamk_f32 v144, v144, 0x3a800000, v118
	v_mfma_f32_32x32x16_bf16 v[48:63], v[120:123], v[124:127], v[48:63]
	v_rsq_f32_e32 v144, v144
	s_nop 1
	v_mfma_f32_32x32x16_bf16 v[32:47], v[120:123], v[128:131], v[32:47]
	ds_bpermute_b32 v156, v153, v144
	ds_bpermute_b32 v157, v153, v144 offset:4
	v_mfma_f32_32x32x16_bf16 v[16:31], v[120:123], v[132:135], v[16:31]
	ds_bpermute_b32 v158, v153, v144 offset:8
	ds_bpermute_b32 v159, v153, v144 offset:12
	v_mfma_f32_32x32x16_bf16 v[0:15], v[120:123], v[136:139], v[0:15]
	ds_bpermute_b32 v160, v153, v144 offset:32
	ds_bpermute_b32 v161, v153, v144 offset:36
	v_mfma_f32_32x32x16_bf16 v[48:63], v[140:143], v[218:221], v[48:63]
	ds_bpermute_b32 v162, v153, v144 offset:40
	ds_bpermute_b32 v163, v153, v144 offset:44
	v_mfma_f32_32x32x16_bf16 v[32:47], v[140:143], v[222:225], v[32:47]
	ds_bpermute_b32 v164, v153, v144 offset:64
	ds_bpermute_b32 v165, v153, v144 offset:68
	v_mfma_f32_32x32x16_bf16 v[16:31], v[140:143], v[226:229], v[16:31]
	ds_bpermute_b32 v166, v153, v144 offset:72
	ds_bpermute_b32 v167, v153, v144 offset:76
	v_mfma_f32_32x32x16_bf16 v[0:15], v[140:143], v[230:233], v[0:15]
	ds_bpermute_b32 v168, v153, v144 offset:96
	ds_bpermute_b32 v169, v153, v144 offset:100
	v_mfma_f32_32x32x16_bf16 v[48:63], v[234:237], v[238:241], v[48:63]
	ds_bpermute_b32 v170, v153, v144 offset:104
	ds_bpermute_b32 v171, v153, v144 offset:108
	v_mfma_f32_32x32x16_bf16 v[32:47], v[234:237], v[242:245], v[32:47]
	v_mfma_f32_32x32x16_bf16 v[16:31], v[234:237], v[246:249], v[16:31]
	v_mfma_f32_32x32x16_bf16 v[0:15], v[234:237], v[250:253], v[0:15]
	s_setprio 0
	s_branch .LBB0_754

.LBB0_836:
	v_add_u32_e32 v148, s68, v160
	v_and_b32_e32 v226, 31, v199
	v_bfe_u32 v227, v199, 5, 1
	v_lshlrev_b32_e32 v229, 2, v227
	v_sub_u32_e32 v226, v226, v229
	v_add_u32_e32 v229, s68, v160
	v_add_lshl_u32 v226, v226, v229, 2
	v_lshlrev_b32_e32 v227, 4, v227
	global_load_dword v144, v226, s[18:19]
	v_add_u32_e32 v229, 0x10000, v226
	global_load_dword v145, v229, s[18:19]
	v_add_u32_e32 v229, 0x20000, v226
	global_load_dword v146, v229, s[18:19]
	v_add_u32_e32 v229, 0x30000, v226
	global_load_dword v147, v229, s[18:19]
	v_add_u32_e32 v229, 0x40000, v226
	global_load_dword v184, v229, s[18:19]
	v_add_u32_e32 v229, 0x50000, v226
	global_load_dword v185, v229, s[18:19]
	v_add_u32_e32 v229, 0x60000, v226
	global_load_dword v186, v229, s[18:19]
	v_add_u32_e32 v229, 0x70000, v226
	global_load_dword v187, v229, s[18:19]
	s_waitcnt vmcnt(0)
	v_add_f32_e32 v144, v144, v145
	v_add_f32_e32 v146, v146, v147
	v_add_f32_e32 v184, v184, v185
	v_add_f32_e32 v186, v186, v187
	v_add_f32_e32 v144, v144, v146
	v_add_f32_e32 v184, v184, v186
	v_add_f32_e32 v144, v144, v184
	v_fmamk_f32 v144, v144, 0x3a800000, v196
	v_rsq_f32_e32 v144, v144
	s_nop 1
	ds_bpermute_b32 v230, v227, v144
	ds_bpermute_b32 v231, v227, v144 offset:4
	ds_bpermute_b32 v232, v227, v144 offset:8
	ds_bpermute_b32 v233, v227, v144 offset:12
	ds_bpermute_b32 v234, v227, v144 offset:32
	ds_bpermute_b32 v235, v227, v144 offset:36
	ds_bpermute_b32 v236, v227, v144 offset:40
	ds_bpermute_b32 v237, v227, v144 offset:44
	ds_bpermute_b32 v238, v227, v144 offset:64
	ds_bpermute_b32 v239, v227, v144 offset:68
	ds_bpermute_b32 v240, v227, v144 offset:72
	ds_bpermute_b32 v241, v227, v144 offset:76
	ds_bpermute_b32 v242, v227, v144 offset:96
	ds_bpermute_b32 v243, v227, v144 offset:100
	ds_bpermute_b32 v244, v227, v144 offset:104
	ds_bpermute_b32 v245, v227, v144 offset:108
	s_waitcnt lgkmcnt(0)
	v_or_b32_e32 v150, 8, v148
	v_or_b32_e32 v152, 9, v148
	v_or_b32_e32 v154, 16, v148
	v_ashrrev_i32_e32 v155, 31, v154
	s_lshl_b64 s[72:73], s[72:73], 2
	s_add_u32 s72, s10, s72
	s_addc_u32 s73, s11, s73
	s_ashr_i32 s8, s86, 3
	v_lshl_add_u64 v[92:93], v[154:155], 2, s[18:19]
	v_or_b32_e32 v84, 24, v148
	v_ashrrev_i32_e32 v85, 31, v84
	v_add_co_u32_e32 v94, vcc, s82, v92
	s_nop 1
	v_addc_co_u32_e32 v95, vcc, 0, v93, vcc
	v_or_b32_e32 v80, 17, v148
	v_ashrrev_i32_e32 v81, 31, v80
	v_lshl_add_u64 v[92:93], v[80:81], 2, s[18:19]
	v_or_b32_e32 v88, 25, v148
	v_ashrrev_i32_e32 v89, 31, v88
	v_or_b32_e32 v66, s0, v140
	v_ashrrev_i32_e32 v67, 31, v66
	v_lshl_add_u64 v[66:67], v[66:67], 2, s[72:73]
	global_load_dword v91, v[66:67], off
	global_load_dword v90, v[66:67], off offset:128
	global_load_dword v105, v[66:67], off offset:256
	global_load_dword v104, v[66:67], off offset:384
	s_and_b32 s72, s86, 7
	s_cmp_gt_i32 s8, 1
	v_mov_b32_e32 v92, v230
	v_mov_b32_e32 v94, v231
	v_mov_b32_e32 v96, v232
	v_mov_b32_e32 v98, v233
	v_mov_b32_e32 v100, v234
	v_mov_b32_e32 v102, v235
	v_mov_b32_e32 v106, v236
	v_mov_b32_e32 v108, v237
	v_mov_b32_e32 v110, v238
	v_mov_b32_e32 v112, v239
	v_mov_b32_e32 v114, v240
	v_mov_b32_e32 v116, v241
	v_mov_b32_e32 v118, v242
	v_mov_b32_e32 v120, v243
	v_mov_b32_e32 v122, v244
	v_mov_b32_e32 v124, v245
	v_mov_b32_e32 v64, v32
	v_mov_b32_e32 v65, v48
	v_mov_b32_e32 v48, v33
	v_mov_b32_e32 v32, v34
	v_mov_b32_e32 v33, v50
	s_waitcnt vmcnt(2)
	v_pk_fma_f32 v[78:79], v[32:33], v[96:97], v[90:91] op_sel_hi:[1,0,1]
	v_mov_b32_e32 v32, v36
	v_mov_b32_e32 v33, v52
	v_pk_fma_f32 v[70:71], v[32:33], v[100:101], v[90:91] op_sel_hi:[1,0,1]
	v_mov_b32_e32 v32, v38
	v_mov_b32_e32 v33, v54
	v_pk_fma_f32 v[76:77], v[32:33], v[106:107], v[90:91] op_sel_hi:[1,0,1]
	v_mov_b32_e32 v32, v40
	v_mov_b32_e32 v33, v56
	v_pk_fma_f32 v[66:67], v[32:33], v[110:111], v[90:91] op_sel_hi:[1,0,1]
	v_mov_b32_e32 v56, v41
	v_mov_b32_e32 v32, v42
	v_mov_b32_e32 v33, v58
	v_pk_fma_f32 v[86:87], v[64:65], v[92:93], v[90:91] op_sel_hi:[1,0,1]
	v_mov_b32_e32 v52, v37
	v_pk_fma_f32 v[64:65], v[56:57], v[112:113], v[90:91] op_sel_hi:[1,0,1]
	v_pk_fma_f32 v[56:57], v[32:33], v[114:115], v[90:91] op_sel_hi:[1,0,1]
	v_mov_b32_e32 v32, v44
	v_mov_b32_e32 v33, v60
	v_pk_fma_f32 v[72:73], v[52:53], v[102:103], v[90:91] op_sel_hi:[1,0,1]
	v_pk_fma_f32 v[52:53], v[32:33], v[118:119], v[90:91] op_sel_hi:[1,0,1]
	v_mov_b32_e32 v32, v46
	v_mov_b32_e32 v33, v62
	v_pk_fma_f32 v[82:83], v[48:49], v[94:95], v[90:91] op_sel_hi:[1,0,1]
	v_pk_fma_f32 v[48:49], v[32:33], v[122:123], v[90:91] op_sel_hi:[1,0,1]
	v_mov_b32_e32 v32, v0
	v_mov_b32_e32 v33, v16
	v_mov_b32_e32 v16, v1
	v_mov_b32_e32 v0, v2
	v_mov_b32_e32 v1, v18
	s_waitcnt vmcnt(0)
	v_pk_fma_f32 v[40:41], v[0:1], v[96:97], v[104:105] op_sel_hi:[1,0,1]
	v_mov_b32_e32 v0, v4
	v_mov_b32_e32 v1, v20
	v_pk_fma_f32 v[36:37], v[0:1], v[100:101], v[104:105] op_sel_hi:[1,0,1]
	v_mov_b32_e32 v0, v6
	v_mov_b32_e32 v1, v22
	v_mov_b32_e32 v60, v45
	v_pk_fma_f32 v[44:45], v[32:33], v[92:93], v[104:105] op_sel_hi:[1,0,1]
	v_mov_b32_e32 v20, v5
	v_pk_fma_f32 v[32:33], v[0:1], v[106:107], v[104:105] op_sel_hi:[1,0,1]
	v_mov_b32_e32 v0, v8
	v_mov_b32_e32 v1, v24
	v_mov_b32_e32 v50, v35
	v_pk_fma_f32 v[34:35], v[20:21], v[102:103], v[104:105] op_sel_hi:[1,0,1]
	v_pk_fma_f32 v[20:21], v[0:1], v[110:111], v[104:105] op_sel_hi:[1,0,1]
	v_mov_b32_e32 v0, v10
	v_mov_b32_e32 v1, v26
	v_mov_b32_e32 v58, v43
	v_pk_fma_f32 v[42:43], v[16:17], v[94:95], v[104:105] op_sel_hi:[1,0,1]
	v_pk_fma_f32 v[16:17], v[0:1], v[114:115], v[104:105] op_sel_hi:[1,0,1]
	v_mov_b32_e32 v0, v12
	v_mov_b32_e32 v1, v28
	v_mov_b32_e32 v54, v39
	v_mov_b32_e32 v62, v47
	v_mov_b32_e32 v18, v3
	v_mov_b32_e32 v22, v7
	v_mov_b32_e32 v24, v9
	v_mov_b32_e32 v26, v11
	v_pk_fma_f32 v[6:7], v[0:1], v[118:119], v[104:105] op_sel_hi:[1,0,1]
	v_mov_b32_e32 v28, v13
	v_mov_b32_e32 v0, v14
	v_mov_b32_e32 v1, v30
	v_mov_b32_e32 v30, v15
	v_pk_fma_f32 v[74:75], v[50:51], v[98:99], v[90:91] op_sel_hi:[1,0,1]
	v_pk_fma_f32 v[68:69], v[54:55], v[108:109], v[90:91] op_sel_hi:[1,0,1]
	v_pk_fma_f32 v[54:55], v[58:59], v[116:117], v[90:91] op_sel_hi:[1,0,1]
	v_pk_fma_f32 v[50:51], v[60:61], v[120:121], v[90:91] op_sel_hi:[1,0,1]
	v_pk_fma_f32 v[46:47], v[62:63], v[124:125], v[90:91] op_sel_hi:[1,0,1]
	v_pk_fma_f32 v[38:39], v[18:19], v[98:99], v[104:105] op_sel_hi:[1,0,1]
	v_pk_fma_f32 v[22:23], v[22:23], v[108:109], v[104:105] op_sel_hi:[1,0,1]
	v_pk_fma_f32 v[18:19], v[24:25], v[112:113], v[104:105] op_sel_hi:[1,0,1]
	v_pk_fma_f32 v[8:9], v[26:27], v[116:117], v[104:105] op_sel_hi:[1,0,1]
	v_pk_fma_f32 v[4:5], v[28:29], v[120:121], v[104:105] op_sel_hi:[1,0,1]
	v_pk_fma_f32 v[2:3], v[0:1], v[122:123], v[104:105] op_sel_hi:[1,0,1]
	v_pk_fma_f32 v[0:1], v[30:31], v[124:125], v[104:105] op_sel_hi:[1,0,1]
	s_mov_b64 s[0:1], -1
	s_cbranch_scc0 .LBB0_846
	s_and_b64 s[0:1], s[4:5], exec
	s_cselect_b32 s0, 0x100, 0
	s_add_i32 s0, s69, s0
	v_add_u32_e32 v27, s0, v160
	s_lshl_b32 s0, s87, 18
	s_lshl_b32 s1, s72, 15
	s_or_b32 s75, s0, s1
	s_lshl_b32 s0, s87, 10
	s_lshl_b32 s73, s72, 7
	s_or_b32 s87, s0, s73
	v_or_b32_e32 v29, s87, v140
	v_mul_lo_u32 v29, v29, s76
	v_or_b32_e32 v28, s75, v161
	v_add_u32_e32 v29, 0x800000, v29
	v_cndmask_b32_e64 v60, v28, v29, s[4:5]
	v_add_u32_e32 v28, v60, v27
	v_ashrrev_i32_e32 v29, 31, v28
	v_cvt_pk_bf16_f32 v30, v87, v83
	v_cvt_pk_bf16_f32 v31, v79, v75
	v_lshl_add_u64 v[28:29], v[28:29], 1, s[20:21]
	global_store_dwordx2 v[28:29], v[30:31], off sc1
	v_or_b32_e32 v28, 8, v27
	v_add_u32_e32 v30, v60, v28
	v_ashrrev_i32_e32 v31, 31, v30
	v_cvt_pk_bf16_f32 v58, v71, v73
	v_cvt_pk_bf16_f32 v59, v77, v69
	v_lshl_add_u64 v[30:31], v[30:31], 1, s[20:21]
	v_or_b32_e32 v29, 16, v27
	global_store_dwordx2 v[30:31], v[58:59], off sc1
	v_add_u32_e32 v30, v60, v29
	v_ashrrev_i32_e32 v31, 31, v30
	v_cvt_pk_bf16_f32 v58, v67, v65
	v_cvt_pk_bf16_f32 v59, v57, v55
	v_lshl_add_u64 v[30:31], v[30:31], 1, s[20:21]
	global_store_dwordx2 v[30:31], v[58:59], off sc1
	v_or_b32_e32 v30, 24, v27
	v_add_u32_e32 v58, v60, v30
	v_ashrrev_i32_e32 v59, 31, v58
	v_cndmask_b32_e64 v31, 0, 1, s[70:71]
	v_or_b32_e32 v26, 1, v148
	v_or_b32_e32 v25, 2, v148
	v_or_b32_e32 v24, 3, v148
	v_or_b32_e32 v15, 10, v148
	v_or_b32_e32 v14, 11, v148
	v_or_b32_e32 v13, 18, v148
	v_or_b32_e32 v12, 19, v148
	v_or_b32_e32 v11, 26, v148
	v_or_b32_e32 v10, 27, v148
	v_cvt_pk_bf16_f32 v60, v53, v51
	v_cvt_pk_bf16_f32 v61, v49, v47
	v_lshl_add_u64 v[58:59], v[58:59], 1, s[20:21]
	v_cmp_ne_u32_e64 s[0:1], 1, v31
	s_andn2_b64 vcc, exec, s[70:71]
	global_store_dwordx2 v[58:59], v[60:61], off sc1
	s_cbranch_vccnz .LBB0_839
	v_or_b32_e32 v31, s73, v140
	v_lshl_or_b32 v58, v148, 10, v31
	v_ashrrev_i32_e32 v59, 31, v58
	v_lshl_add_u64 v[58:59], v[58:59], 2, s[22:23]
	global_store_dword v[58:59], v87, off sc1
	v_lshl_or_b32 v58, v26, 10, v31
	v_ashrrev_i32_e32 v59, 31, v58
	v_lshl_add_u64 v[58:59], v[58:59], 2, s[22:23]
	global_store_dword v[58:59], v83, off sc1
	v_lshl_or_b32 v58, v25, 10, v31
	v_ashrrev_i32_e32 v59, 31, v58
	v_lshl_add_u64 v[58:59], v[58:59], 2, s[22:23]
	global_store_dword v[58:59], v79, off sc1
	v_lshl_or_b32 v58, v24, 10, v31
	v_ashrrev_i32_e32 v59, 31, v58
	v_lshl_add_u64 v[58:59], v[58:59], 2, s[22:23]
	global_store_dword v[58:59], v75, off sc1
	v_lshl_or_b32 v58, v150, 10, v31
	v_ashrrev_i32_e32 v59, 31, v58
	v_lshl_add_u64 v[58:59], v[58:59], 2, s[22:23]
	global_store_dword v[58:59], v71, off sc1
	v_lshl_or_b32 v58, v152, 10, v31
	v_ashrrev_i32_e32 v59, 31, v58
	v_lshl_add_u64 v[58:59], v[58:59], 2, s[22:23]
	global_store_dword v[58:59], v73, off sc1
	v_lshl_or_b32 v58, v15, 10, v31
	v_ashrrev_i32_e32 v59, 31, v58
	v_lshl_add_u64 v[58:59], v[58:59], 2, s[22:23]
	global_store_dword v[58:59], v77, off sc1
	v_lshl_or_b32 v58, v14, 10, v31
	v_ashrrev_i32_e32 v59, 31, v58
	v_lshl_add_u64 v[58:59], v[58:59], 2, s[22:23]
	global_store_dword v[58:59], v69, off sc1
	v_lshl_or_b32 v58, v154, 10, v31
	v_ashrrev_i32_e32 v59, 31, v58
	v_lshl_add_u64 v[58:59], v[58:59], 2, s[22:23]
	global_store_dword v[58:59], v67, off sc1
	v_lshl_or_b32 v58, v80, 10, v31
	v_ashrrev_i32_e32 v59, 31, v58
	v_lshl_add_u64 v[58:59], v[58:59], 2, s[22:23]
	global_store_dword v[58:59], v65, off sc1
	v_lshl_or_b32 v58, v13, 10, v31
	v_ashrrev_i32_e32 v59, 31, v58
	v_lshl_add_u64 v[58:59], v[58:59], 2, s[22:23]
	global_store_dword v[58:59], v57, off sc1
	v_lshl_or_b32 v58, v12, 10, v31
	v_ashrrev_i32_e32 v59, 31, v58
	v_lshl_add_u64 v[58:59], v[58:59], 2, s[22:23]
	global_store_dword v[58:59], v55, off sc1
	v_lshl_or_b32 v58, v84, 10, v31
	v_ashrrev_i32_e32 v59, 31, v58
	v_lshl_add_u64 v[58:59], v[58:59], 2, s[22:23]
	global_store_dword v[58:59], v53, off sc1
	v_lshl_or_b32 v58, v88, 10, v31
	v_ashrrev_i32_e32 v59, 31, v58
	v_lshl_add_u64 v[58:59], v[58:59], 2, s[22:23]
	global_store_dword v[58:59], v51, off sc1
	v_lshl_or_b32 v58, v11, 10, v31
	v_ashrrev_i32_e32 v59, 31, v58
	v_lshl_add_u64 v[58:59], v[58:59], 2, s[22:23]
	global_store_dword v[58:59], v49, off sc1
	v_lshl_or_b32 v58, v10, 10, v31
	v_ashrrev_i32_e32 v59, 31, v58
	v_lshl_add_u64 v[58:59], v[58:59], 2, s[22:23]
	global_store_dword v[58:59], v47, off sc1

.Lmap_done_1_pf_p12:
	s_lshl_b32 s44, s41, 7
	s_lshl_b32 s42, s50, 7
	s_ashr_i32 s45, s44, 31
	s_ashr_i32 s43, s42, 31
	s_lshl_b64 s[46:47], s[44:45], 11
	s_lshl_b64 s[48:49], s[42:43], 11
	s_lshl_b32 s38, s44, 11
	s_add_u32 s18, s14, s38
	s_addc_u32 s19, s15, 0
	s_add_u32 s18, s18, 0x679f000
	s_addc_u32 s19, s19, 0
	s_add_u32 s20, s18, 0x10000
	s_addc_u32 s21, s19, 0
	s_add_u32 s22, s20, 0x10000
	s_addc_u32 s23, s21, 0
	s_add_u32 s24, s22, 0x10000
	s_addc_u32 s25, s23, 0
	s_lshl_b32 s38, s42, 11
	s_add_u32 s26, s14, s38
	s_addc_u32 s27, s15, 0
	s_add_u32 s26, s26, 0x24a0000
	s_addc_u32 s27, s27, 0
	s_add_u32 s28, s26, 0x10000
	s_addc_u32 s29, s27, 0
	s_add_u32 s30, s28, 0x10000
	s_addc_u32 s31, s29, 0
	s_add_u32 s34, s30, 0x10000
	s_addc_u32 s35, s31, 0
	v_mov_b32_e32 v254, v76
	s_mov_b32 s39, 1
	s_waitcnt vmcnt(8)
	s_barrier
	ds_read_b128 v[64:67], v110
	ds_read_b128 v[68:71], v111 offset:16384
	ds_read_b128 v[72:75], v111 offset:20480
	ds_read_b128 v[82:85], v111 offset:24576
	ds_read_b128 v[86:89], v111 offset:28672
	ds_read_b128 v[120:123], v112
	ds_read_b128 v[124:127], v113 offset:16384
	ds_read_b128 v[128:131], v113 offset:20480
	ds_read_b128 v[132:135], v113 offset:24576
	ds_read_b128 v[136:139], v113 offset:28672
	ds_read_b128 v[140:143], v114
	ds_read_b128 v[218:221], v115 offset:16384
	ds_read_b128 v[222:225], v115 offset:20480
	ds_read_b128 v[226:229], v115 offset:24576
	ds_read_b128 v[230:233], v115 offset:28672
	ds_read_b128 v[234:237], v116
	ds_read_b128 v[238:241], v117 offset:16384
	ds_read_b128 v[242:245], v117 offset:20480
	ds_read_b128 v[246:249], v117 offset:24576
	ds_read_b128 v[250:253], v117 offset:28672
	s_waitcnt lgkmcnt(0)
	s_barrier
	s_mov_b32 m0, s36
	s_setprio 1
	v_mfma_f32_32x32x16_bf16 v[48:63], v[64:67], v[68:71], v[48:63]
	v_mfma_f32_32x32x16_bf16 v[32:47], v[64:67], v[72:75], v[32:47]
	global_load_lds_dwordx4 v254, s[18:19]
	s_add_u32 m0, m0, 0x1000
	v_mfma_f32_32x32x16_bf16 v[16:31], v[64:67], v[82:85], v[16:31]
	v_mfma_f32_32x32x16_bf16 v[0:15], v[64:67], v[86:89], v[0:15]
	global_load_lds_dwordx4 v254, s[20:21]
	s_add_u32 m0, m0, 0x1000
	v_mfma_f32_32x32x16_bf16 v[48:63], v[120:123], v[124:127], v[48:63]
	v_mfma_f32_32x32x16_bf16 v[32:47], v[120:123], v[128:131], v[32:47]
	global_load_lds_dwordx4 v254, s[22:23]
	s_add_u32 m0, m0, 0x1000
	v_mfma_f32_32x32x16_bf16 v[16:31], v[120:123], v[132:135], v[16:31]
	v_mfma_f32_32x32x16_bf16 v[0:15], v[120:123], v[136:139], v[0:15]
	global_load_lds_dwordx4 v254, s[24:25]
	s_add_u32 m0, m0, 0x1000
	v_mfma_f32_32x32x16_bf16 v[48:63], v[140:143], v[218:221], v[48:63]
	v_mfma_f32_32x32x16_bf16 v[32:47], v[140:143], v[222:225], v[32:47]
	global_load_lds_dwordx4 v254, s[26:27]
	s_add_u32 m0, m0, 0x1000
	v_mfma_f32_32x32x16_bf16 v[16:31], v[140:143], v[226:229], v[16:31]
	v_mfma_f32_32x32x16_bf16 v[0:15], v[140:143], v[230:233], v[0:15]
	global_load_lds_dwordx4 v254, s[28:29]
	s_add_u32 m0, m0, 0x1000
	v_mfma_f32_32x32x16_bf16 v[48:63], v[234:237], v[238:241], v[48:63]
	v_mfma_f32_32x32x16_bf16 v[32:47], v[234:237], v[242:245], v[32:47]
	global_load_lds_dwordx4 v254, s[30:31]
	s_add_u32 m0, m0, 0x1000
	v_mfma_f32_32x32x16_bf16 v[16:31], v[234:237], v[246:249], v[16:31]
	v_mfma_f32_32x32x16_bf16 v[0:15], v[234:237], v[250:253], v[0:15]
	global_load_lds_dwordx4 v254, s[34:35]
	s_setprio 0
	v_add_u32_e32 v254, 0x80, v254
	s_waitcnt vmcnt(8)
	s_barrier
	ds_read_b128 v[64:67], v110 offset:32768
	ds_read_b128 v[68:71], v111 offset:49152
	ds_read_b128 v[72:75], v111 offset:53248
	ds_read_b128 v[82:85], v111 offset:57344
	ds_read_b128 v[86:89], v111 offset:61440
	ds_read_b128 v[120:123], v112 offset:32768
	ds_read_b128 v[124:127], v113 offset:49152
	ds_read_b128 v[128:131], v113 offset:53248
	ds_read_b128 v[132:135], v113 offset:57344
	ds_read_b128 v[136:139], v113 offset:61440
	ds_read_b128 v[140:143], v114 offset:32768
	ds_read_b128 v[218:221], v115 offset:49152
	ds_read_b128 v[222:225], v115 offset:53248
	ds_read_b128 v[226:229], v115 offset:57344
	ds_read_b128 v[230:233], v115 offset:61440
	ds_read_b128 v[234:237], v116 offset:32768
	ds_read_b128 v[238:241], v117 offset:49152
	ds_read_b128 v[242:245], v117 offset:53248
	ds_read_b128 v[246:249], v117 offset:57344
	ds_read_b128 v[250:253], v117 offset:61440
	s_waitcnt lgkmcnt(0)
	s_barrier
	s_add_u32 m0, s36, 0x8000
	s_setprio 1
	v_mfma_f32_32x32x16_bf16 v[48:63], v[64:67], v[68:71], v[48:63]
	v_add_f32_e32 v144, v144, v145
	v_add_f32_e32 v146, v146, v147
	v_mfma_f32_32x32x16_bf16 v[32:47], v[64:67], v[72:75], v[32:47]
	v_add_f32_e32 v148, v148, v149
	v_add_f32_e32 v150, v150, v151
	global_load_lds_dwordx4 v254, s[18:19]
	s_add_u32 m0, m0, 0x1000
	v_mfma_f32_32x32x16_bf16 v[16:31], v[64:67], v[82:85], v[16:31]
	v_add_f32_e32 v144, v144, v146
	v_add_f32_e32 v148, v148, v150
	v_mfma_f32_32x32x16_bf16 v[0:15], v[64:67], v[86:89], v[0:15]
	v_add_f32_e32 v144, v144, v148
	v_fmamk_f32 v144, v144, 0x3a800000, v118
	global_load_lds_dwordx4 v254, s[20:21]
	s_add_u32 m0, m0, 0x1000
	v_mfma_f32_32x32x16_bf16 v[48:63], v[120:123], v[124:127], v[48:63]
	v_rsq_f32_e32 v144, v144
	s_nop 1
	v_mfma_f32_32x32x16_bf16 v[32:47], v[120:123], v[128:131], v[32:47]
	ds_bpermute_b32 v156, v153, v144
	ds_bpermute_b32 v157, v153, v144 offset:4
	global_load_lds_dwordx4 v254, s[22:23]
	s_add_u32 m0, m0, 0x1000
	v_mfma_f32_32x32x16_bf16 v[16:31], v[120:123], v[132:135], v[16:31]
	ds_bpermute_b32 v158, v153, v144 offset:8
	ds_bpermute_b32 v159, v153, v144 offset:12
	v_mfma_f32_32x32x16_bf16 v[0:15], v[120:123], v[136:139], v[0:15]
	ds_bpermute_b32 v160, v153, v144 offset:32
	ds_bpermute_b32 v161, v153, v144 offset:36
	global_load_lds_dwordx4 v254, s[24:25]
	s_add_u32 m0, m0, 0x1000
	v_mfma_f32_32x32x16_bf16 v[48:63], v[140:143], v[218:221], v[48:63]
	ds_bpermute_b32 v162, v153, v144 offset:40
	ds_bpermute_b32 v163, v153, v144 offset:44
	v_mfma_f32_32x32x16_bf16 v[32:47], v[140:143], v[222:225], v[32:47]
	ds_bpermute_b32 v164, v153, v144 offset:64
	ds_bpermute_b32 v165, v153, v144 offset:68
	global_load_lds_dwordx4 v254, s[26:27]
	s_add_u32 m0, m0, 0x1000
	v_mfma_f32_32x32x16_bf16 v[16:31], v[140:143], v[226:229], v[16:31]
	ds_bpermute_b32 v166, v153, v144 offset:72
	ds_bpermute_b32 v167, v153, v144 offset:76
	v_mfma_f32_32x32x16_bf16 v[0:15], v[140:143], v[230:233], v[0:15]
	ds_bpermute_b32 v168, v153, v144 offset:96
	ds_bpermute_b32 v169, v153, v144 offset:100
	global_load_lds_dwordx4 v254, s[28:29]
	s_add_u32 m0, m0, 0x1000
	v_mfma_f32_32x32x16_bf16 v[48:63], v[234:237], v[238:241], v[48:63]
	ds_bpermute_b32 v170, v153, v144 offset:104
	ds_bpermute_b32 v171, v153, v144 offset:108
	v_mfma_f32_32x32x16_bf16 v[32:47], v[234:237], v[242:245], v[32:47]
	global_load_lds_dwordx4 v254, s[30:31]
	s_add_u32 m0, m0, 0x1000
	v_mfma_f32_32x32x16_bf16 v[16:31], v[234:237], v[246:249], v[16:31]
	v_mfma_f32_32x32x16_bf16 v[0:15], v[234:237], v[250:253], v[0:15]
	global_load_lds_dwordx4 v254, s[34:35]
	s_setprio 0
	v_add_u32_e32 v254, 0x80, v254
	s_branch .LBB0_1097

.LBB0_1179:
	v_add_u32_e32 v118, s66, v133
	v_and_b32_e32 v226, 31, v199
	v_bfe_u32 v227, v199, 5, 1
	v_lshlrev_b32_e32 v229, 2, v227
	v_sub_u32_e32 v226, v226, v229
	v_add_u32_e32 v229, s66, v133
	v_add_lshl_u32 v226, v226, v229, 2
	v_lshlrev_b32_e32 v227, 4, v227
	global_load_dword v112, v226, s[18:19]
	v_add_u32_e32 v229, 0x10000, v226
	global_load_dword v113, v229, s[18:19]
	v_add_u32_e32 v229, 0x20000, v226
	global_load_dword v114, v229, s[18:19]
	v_add_u32_e32 v229, 0x30000, v226
	global_load_dword v115, v229, s[18:19]
	v_add_u32_e32 v229, 0x40000, v226
	global_load_dword v158, v229, s[18:19]
	v_add_u32_e32 v229, 0x50000, v226
	global_load_dword v159, v229, s[18:19]
	v_add_u32_e32 v229, 0x60000, v226
	global_load_dword v160, v229, s[18:19]
	v_add_u32_e32 v229, 0x70000, v226
	global_load_dword v161, v229, s[18:19]
	s_waitcnt vmcnt(0)
	v_add_f32_e32 v112, v112, v113
	v_add_f32_e32 v114, v114, v115
	v_add_f32_e32 v158, v158, v159
	v_add_f32_e32 v160, v160, v161
	v_add_f32_e32 v112, v112, v114
	v_add_f32_e32 v158, v158, v160
	v_add_f32_e32 v112, v112, v158
	v_fmamk_f32 v112, v112, 0x3a800000, v166
	v_rsq_f32_e32 v112, v112
	s_nop 1
	ds_bpermute_b32 v230, v227, v112
	ds_bpermute_b32 v231, v227, v112 offset:4
	ds_bpermute_b32 v232, v227, v112 offset:8
	ds_bpermute_b32 v233, v227, v112 offset:12
	ds_bpermute_b32 v234, v227, v112 offset:32
	ds_bpermute_b32 v235, v227, v112 offset:36
	ds_bpermute_b32 v236, v227, v112 offset:40
	ds_bpermute_b32 v237, v227, v112 offset:44
	ds_bpermute_b32 v238, v227, v112 offset:64
	ds_bpermute_b32 v239, v227, v112 offset:68
	ds_bpermute_b32 v240, v227, v112 offset:72
	ds_bpermute_b32 v241, v227, v112 offset:76
	ds_bpermute_b32 v242, v227, v112 offset:96
	ds_bpermute_b32 v243, v227, v112 offset:100
	ds_bpermute_b32 v244, v227, v112 offset:104
	ds_bpermute_b32 v245, v227, v112 offset:108
	s_waitcnt lgkmcnt(0)
	v_or_b32_e32 v120, 8, v118
	v_or_b32_e32 v122, 9, v118
	s_lshl_b64 s[70:71], s[70:71], 2
	s_add_u32 s70, s10, s70
	s_addc_u32 s71, s11, s71
	s_cmpk_gt_i32 s85, 0x4f
	v_or_b32_e32 v124, 16, v118
	v_or_b32_e32 v126, 17, v118
	v_or_b32_e32 v84, 24, v118
	v_or_b32_e32 v104, 25, v118
	v_or_b32_e32 v66, s4, v108
	v_ashrrev_i32_e32 v67, 31, v66
	v_lshl_add_u64 v[66:67], v[66:67], 2, s[70:71]
	global_load_dword v97, v[66:67], off
	global_load_dword v96, v[66:67], off offset:128
	global_load_dword v95, v[66:67], off offset:256
	global_load_dword v94, v[66:67], off offset:384
	s_mov_b64 s[4:5], -1
	v_mov_b32_e32 v68, v232
	v_mov_b32_e32 v70, v233
	v_mov_b32_e32 v64, v230
	v_mov_b32_e32 v74, v234
	v_mov_b32_e32 v98, v235
	v_mov_b32_e32 v100, v236
	v_mov_b32_e32 v102, v237
	v_mov_b32_e32 v72, v32
	v_mov_b32_e32 v73, v48
	v_mov_b32_e32 v106, v238
	v_mov_b32_e32 v172, v239
	v_mov_b32_e32 v66, v231
	v_mov_b32_e32 v174, v240
	v_mov_b32_e32 v176, v241
	v_mov_b32_e32 v178, v242
	s_waitcnt vmcnt(2)
	v_pk_fma_f32 v[90:91], v[72:73], v[64:65], v[96:97] op_sel_hi:[1,0,1]
	v_mov_b32_e32 v72, v0
	v_mov_b32_e32 v73, v16
	v_mov_b32_e32 v16, v1
	v_mov_b32_e32 v0, v34
	v_mov_b32_e32 v1, v50
	v_pk_fma_f32 v[80:81], v[0:1], v[68:69], v[96:97] op_sel_hi:[1,0,1]
	v_mov_b32_e32 v0, v2
	v_mov_b32_e32 v1, v18
	s_waitcnt vmcnt(0)
	v_pk_fma_f32 v[82:83], v[0:1], v[68:69], v[94:95] op_sel_hi:[1,0,1]
	v_mov_b32_e32 v0, v36
	v_mov_b32_e32 v1, v52
	v_pk_fma_f32 v[92:93], v[72:73], v[64:65], v[94:95] op_sel_hi:[1,0,1]
	v_pk_fma_f32 v[72:73], v[0:1], v[74:75], v[96:97] op_sel_hi:[1,0,1]
	v_mov_b32_e32 v0, v4
	v_mov_b32_e32 v1, v20
	v_pk_fma_f32 v[74:75], v[0:1], v[74:75], v[94:95] op_sel_hi:[1,0,1]
	v_mov_b32_e32 v0, v38
	v_mov_b32_e32 v1, v54
	v_mov_b32_e32 v180, v243
	v_mov_b32_e32 v184, v245
	v_mov_b32_e32 v48, v33
	v_pk_fma_f32 v[64:65], v[0:1], v[100:101], v[96:97] op_sel_hi:[1,0,1]
	v_mov_b32_e32 v0, v6
	v_mov_b32_e32 v1, v22
	v_mov_b32_e32 v182, v244
	v_pk_fma_f32 v[88:89], v[48:49], v[66:67], v[96:97] op_sel_hi:[1,0,1]
	v_pk_fma_f32 v[86:87], v[16:17], v[66:67], v[94:95] op_sel_hi:[1,0,1]
	v_pk_fma_f32 v[66:67], v[0:1], v[100:101], v[94:95] op_sel_hi:[1,0,1]
	v_mov_b32_e32 v0, v40
	v_mov_b32_e32 v1, v56
	v_mov_b32_e32 v54, v39
	v_pk_fma_f32 v[38:39], v[0:1], v[106:107], v[96:97] op_sel_hi:[1,0,1]
	v_mov_b32_e32 v0, v8
	v_mov_b32_e32 v1, v24
	v_pk_fma_f32 v[48:49], v[0:1], v[106:107], v[94:95] op_sel_hi:[1,0,1]
	v_mov_b32_e32 v24, v9
	v_mov_b32_e32 v0, v42
	v_mov_b32_e32 v1, v58
	v_mov_b32_e32 v52, v37
	v_pk_fma_f32 v[36:37], v[24:25], v[172:173], v[94:95] op_sel_hi:[1,0,1]
	v_pk_fma_f32 v[24:25], v[0:1], v[174:175], v[96:97] op_sel_hi:[1,0,1]
	v_mov_b32_e32 v0, v10
	v_mov_b32_e32 v1, v26
	v_pk_fma_f32 v[32:33], v[0:1], v[174:175], v[94:95] op_sel_hi:[1,0,1]
	v_mov_b32_e32 v0, v44
	v_mov_b32_e32 v1, v60
	v_mov_b32_e32 v18, v3
	v_pk_fma_f32 v[16:17], v[0:1], v[178:179], v[96:97] op_sel_hi:[1,0,1]
	v_mov_b32_e32 v0, v12
	v_mov_b32_e32 v1, v28
	v_pk_fma_f32 v[78:79], v[18:19], v[70:71], v[94:95] op_sel_hi:[1,0,1]
	v_pk_fma_f32 v[18:19], v[0:1], v[178:179], v[94:95] op_sel_hi:[1,0,1]
	v_mov_b32_e32 v0, v46
	v_mov_b32_e32 v1, v62
	v_mov_b32_e32 v50, v35
	v_mov_b32_e32 v20, v5
	v_mov_b32_e32 v22, v7
	v_mov_b32_e32 v56, v41
	v_mov_b32_e32 v58, v43
	v_mov_b32_e32 v26, v11
	v_mov_b32_e32 v60, v45
	v_mov_b32_e32 v28, v13
	v_pk_fma_f32 v[4:5], v[0:1], v[182:183], v[96:97] op_sel_hi:[1,0,1]
	v_mov_b32_e32 v0, v14
	v_mov_b32_e32 v1, v30
	v_mov_b32_e32 v62, v47
	v_mov_b32_e32 v30, v15
	v_pk_fma_f32 v[76:77], v[50:51], v[70:71], v[96:97] op_sel_hi:[1,0,1]
	v_pk_fma_f32 v[68:69], v[52:53], v[98:99], v[96:97] op_sel_hi:[1,0,1]
	v_pk_fma_f32 v[70:71], v[20:21], v[98:99], v[94:95] op_sel_hi:[1,0,1]
	v_pk_fma_f32 v[50:51], v[54:55], v[102:103], v[96:97] op_sel_hi:[1,0,1]
	v_pk_fma_f32 v[52:53], v[22:23], v[102:103], v[94:95] op_sel_hi:[1,0,1]
	v_pk_fma_f32 v[34:35], v[56:57], v[172:173], v[96:97] op_sel_hi:[1,0,1]
	v_pk_fma_f32 v[20:21], v[58:59], v[176:177], v[96:97] op_sel_hi:[1,0,1]
	v_pk_fma_f32 v[22:23], v[26:27], v[176:177], v[94:95] op_sel_hi:[1,0,1]
	v_pk_fma_f32 v[8:9], v[60:61], v[180:181], v[96:97] op_sel_hi:[1,0,1]
	v_pk_fma_f32 v[10:11], v[28:29], v[180:181], v[94:95] op_sel_hi:[1,0,1]
	v_pk_fma_f32 v[6:7], v[0:1], v[182:183], v[94:95] op_sel_hi:[1,0,1]
	v_pk_fma_f32 v[0:1], v[62:63], v[184:185], v[96:97] op_sel_hi:[1,0,1]
	v_pk_fma_f32 v[2:3], v[30:31], v[184:185], v[94:95] op_sel_hi:[1,0,1]
	s_cbranch_scc0 .LBB0_1189
	s_add_i32 s8, s84, -10
	s_and_b64 s[4:5], s[0:1], exec
	s_cselect_b32 s4, 0x100, 0
	s_add_i32 s4, s67, s4
	v_add_u32_e32 v31, s4, v133
	s_lshl_b32 s4, s8, 15
	s_lshl_b32 s71, s86, 8
	s_lshl_b32 s8, s8, 7
	s_add_i32 s71, s71, s8
	s_lshl_b32 s70, s86, 16
	v_or_b32_e32 v41, s71, v108
	s_add_i32 s70, s70, s4
	v_mul_lo_u32 v41, v41, s74
	v_or_b32_e32 v40, s70, v134
	v_add_u32_e32 v41, 0x200000, v41
	v_cndmask_b32_e64 v46, v40, v41, s[0:1]
	v_add_u32_e32 v40, v46, v31
	v_ashrrev_i32_e32 v41, 31, v40
	v_cvt_pk_bf16_f32 v42, v91, v89
	v_cvt_pk_bf16_f32 v43, v81, v77
	v_lshl_add_u64 v[40:41], v[40:41], 1, s[20:21]
	global_store_dwordx2 v[40:41], v[42:43], off sc1
	v_or_b32_e32 v40, 8, v31
	v_add_u32_e32 v42, v46, v40
	v_ashrrev_i32_e32 v43, 31, v42
	v_cvt_pk_bf16_f32 v44, v73, v69
	v_cvt_pk_bf16_f32 v45, v65, v51
	v_lshl_add_u64 v[42:43], v[42:43], 1, s[20:21]
	v_or_b32_e32 v41, 16, v31
	global_store_dwordx2 v[42:43], v[44:45], off sc1
	v_add_u32_e32 v42, v46, v41
	v_ashrrev_i32_e32 v43, 31, v42
	v_cvt_pk_bf16_f32 v44, v39, v35
	v_cvt_pk_bf16_f32 v45, v25, v21
	v_lshl_add_u64 v[42:43], v[42:43], 1, s[20:21]
	global_store_dwordx2 v[42:43], v[44:45], off sc1
	v_or_b32_e32 v42, 24, v31
	v_add_u32_e32 v44, v46, v42
	v_ashrrev_i32_e32 v45, 31, v44
	v_cndmask_b32_e64 v43, 0, 1, s[68:69]
	v_or_b32_e32 v30, 1, v118
	v_or_b32_e32 v29, 2, v118
	v_or_b32_e32 v28, 3, v118
	v_or_b32_e32 v27, 10, v118
	v_or_b32_e32 v26, 11, v118
	v_or_b32_e32 v15, 18, v118
	v_or_b32_e32 v14, 19, v118
	v_or_b32_e32 v13, 26, v118
	v_or_b32_e32 v12, 27, v118
	v_cvt_pk_bf16_f32 v46, v17, v9
	v_cvt_pk_bf16_f32 v47, v5, v1
	v_lshl_add_u64 v[44:45], v[44:45], 1, s[20:21]
	v_cmp_ne_u32_e64 s[4:5], 1, v43
	s_andn2_b64 vcc, exec, s[68:69]
	global_store_dwordx2 v[44:45], v[46:47], off sc1
	s_cbranch_vccnz .LBB0_1182
	v_or_b32_e32 v43, s8, v108
	v_lshl_add_u32 v44, v118, 8, v43
	v_ashrrev_i32_e32 v45, 31, v44
	v_lshl_add_u64 v[44:45], v[44:45], 2, s[22:23]
	global_store_dword v[44:45], v91, off sc1
	v_lshl_add_u32 v44, v30, 8, v43
	v_ashrrev_i32_e32 v45, 31, v44
	v_lshl_add_u64 v[44:45], v[44:45], 2, s[22:23]
	global_store_dword v[44:45], v89, off sc1
	v_lshl_add_u32 v44, v29, 8, v43
	v_ashrrev_i32_e32 v45, 31, v44
	v_lshl_add_u64 v[44:45], v[44:45], 2, s[22:23]
	global_store_dword v[44:45], v81, off sc1
	v_lshl_add_u32 v44, v28, 8, v43
	v_ashrrev_i32_e32 v45, 31, v44
	v_lshl_add_u64 v[44:45], v[44:45], 2, s[22:23]
	global_store_dword v[44:45], v77, off sc1
	v_lshl_add_u32 v44, v120, 8, v43
	v_ashrrev_i32_e32 v45, 31, v44
	v_lshl_add_u64 v[44:45], v[44:45], 2, s[22:23]
	global_store_dword v[44:45], v73, off sc1
	v_lshl_add_u32 v44, v122, 8, v43
	v_ashrrev_i32_e32 v45, 31, v44
	v_lshl_add_u64 v[44:45], v[44:45], 2, s[22:23]
	global_store_dword v[44:45], v69, off sc1
	v_lshl_add_u32 v44, v27, 8, v43
	v_ashrrev_i32_e32 v45, 31, v44
	v_lshl_add_u64 v[44:45], v[44:45], 2, s[22:23]
	global_store_dword v[44:45], v65, off sc1
	v_lshl_add_u32 v44, v26, 8, v43
	v_ashrrev_i32_e32 v45, 31, v44
	v_lshl_add_u64 v[44:45], v[44:45], 2, s[22:23]
	global_store_dword v[44:45], v51, off sc1
	v_lshl_add_u32 v44, v124, 8, v43
	v_ashrrev_i32_e32 v45, 31, v44
	v_lshl_add_u64 v[44:45], v[44:45], 2, s[22:23]
	global_store_dword v[44:45], v39, off sc1
	v_lshl_add_u32 v44, v126, 8, v43
	v_ashrrev_i32_e32 v45, 31, v44
	v_lshl_add_u64 v[44:45], v[44:45], 2, s[22:23]
	global_store_dword v[44:45], v35, off sc1
	v_lshl_add_u32 v44, v15, 8, v43
	v_ashrrev_i32_e32 v45, 31, v44
	v_lshl_add_u64 v[44:45], v[44:45], 2, s[22:23]
	global_store_dword v[44:45], v25, off sc1
	v_lshl_add_u32 v44, v14, 8, v43
	v_ashrrev_i32_e32 v45, 31, v44
	v_lshl_add_u64 v[44:45], v[44:45], 2, s[22:23]
	global_store_dword v[44:45], v21, off sc1
	v_lshl_add_u32 v44, v84, 8, v43
	v_ashrrev_i32_e32 v45, 31, v44
	v_lshl_add_u64 v[44:45], v[44:45], 2, s[22:23]
	global_store_dword v[44:45], v17, off sc1
	v_lshl_add_u32 v44, v104, 8, v43
	v_ashrrev_i32_e32 v45, 31, v44
	v_lshl_add_u64 v[44:45], v[44:45], 2, s[22:23]
	global_store_dword v[44:45], v9, off sc1
	v_lshl_add_u32 v44, v13, 8, v43
	v_ashrrev_i32_e32 v45, 31, v44
	v_lshl_add_u64 v[44:45], v[44:45], 2, s[22:23]
	global_store_dword v[44:45], v5, off sc1
	v_lshl_add_u32 v44, v12, 8, v43
	v_ashrrev_i32_e32 v45, 31, v44
	v_lshl_add_u64 v[44:45], v[44:45], 2, s[22:23]
	global_store_dword v[44:45], v1, off sc1

.Lmap_done_2_pf_p17:
	s_lshl_b32 s44, s41, 7
	s_lshl_b32 s42, s50, 7
	s_ashr_i32 s45, s44, 31
	s_ashr_i32 s43, s42, 31
	s_lshl_b64 s[46:47], s[44:45], 11
	s_lshl_b64 s[48:49], s[42:43], 11
	s_lshl_b32 s38, s44, 11
	s_add_u32 s18, s14, s38
	s_addc_u32 s19, s15, 0
	s_add_u32 s18, s18, 0x679f000
	s_addc_u32 s19, s19, 0
	s_add_u32 s20, s18, 0x10000
	s_addc_u32 s21, s19, 0
	s_add_u32 s22, s20, 0x10000
	s_addc_u32 s23, s21, 0
	s_add_u32 s24, s22, 0x10000
	s_addc_u32 s25, s23, 0
	s_lshl_b32 s38, s42, 11
	s_add_u32 s26, s14, s38
	s_addc_u32 s27, s15, 0
	s_add_u32 s26, s26, 0x2fa0000
	s_addc_u32 s27, s27, 0
	s_add_u32 s28, s26, 0x10000
	s_addc_u32 s29, s27, 0
	s_add_u32 s30, s28, 0x10000
	s_addc_u32 s31, s29, 0
	s_add_u32 s34, s30, 0x10000
	s_addc_u32 s35, s31, 0
	v_mov_b32_e32 v254, v76
	s_mov_b32 s39, 1
	s_waitcnt vmcnt(8)
	s_barrier
	ds_read_b128 v[64:67], v110
	ds_read_b128 v[68:71], v111 offset:16384
	ds_read_b128 v[72:75], v111 offset:20480
	ds_read_b128 v[82:85], v111 offset:24576
	ds_read_b128 v[86:89], v111 offset:28672
	ds_read_b128 v[120:123], v112
	ds_read_b128 v[124:127], v113 offset:16384
	ds_read_b128 v[128:131], v113 offset:20480
	ds_read_b128 v[132:135], v113 offset:24576
	ds_read_b128 v[136:139], v113 offset:28672
	ds_read_b128 v[140:143], v114
	ds_read_b128 v[218:221], v115 offset:16384
	ds_read_b128 v[222:225], v115 offset:20480
	ds_read_b128 v[226:229], v115 offset:24576
	ds_read_b128 v[230:233], v115 offset:28672
	ds_read_b128 v[234:237], v116
	ds_read_b128 v[238:241], v117 offset:16384
	ds_read_b128 v[242:245], v117 offset:20480
	ds_read_b128 v[246:249], v117 offset:24576
	ds_read_b128 v[250:253], v117 offset:28672
	s_waitcnt lgkmcnt(0)
	s_barrier
	s_mov_b32 m0, s36
	s_setprio 1
	v_mfma_f32_32x32x16_bf16 v[48:63], v[64:67], v[68:71], v[48:63]
	v_mfma_f32_32x32x16_bf16 v[32:47], v[64:67], v[72:75], v[32:47]
	global_load_lds_dwordx4 v254, s[18:19]
	s_add_u32 m0, m0, 0x1000
	v_mfma_f32_32x32x16_bf16 v[16:31], v[64:67], v[82:85], v[16:31]
	v_mfma_f32_32x32x16_bf16 v[0:15], v[64:67], v[86:89], v[0:15]
	global_load_lds_dwordx4 v254, s[20:21]
	s_add_u32 m0, m0, 0x1000
	v_mfma_f32_32x32x16_bf16 v[48:63], v[120:123], v[124:127], v[48:63]
	v_mfma_f32_32x32x16_bf16 v[32:47], v[120:123], v[128:131], v[32:47]
	global_load_lds_dwordx4 v254, s[22:23]
	s_add_u32 m0, m0, 0x1000
	v_mfma_f32_32x32x16_bf16 v[16:31], v[120:123], v[132:135], v[16:31]
	v_mfma_f32_32x32x16_bf16 v[0:15], v[120:123], v[136:139], v[0:15]
	global_load_lds_dwordx4 v254, s[24:25]
	s_add_u32 m0, m0, 0x1000
	v_mfma_f32_32x32x16_bf16 v[48:63], v[140:143], v[218:221], v[48:63]
	v_mfma_f32_32x32x16_bf16 v[32:47], v[140:143], v[222:225], v[32:47]
	global_load_lds_dwordx4 v254, s[26:27]
	s_add_u32 m0, m0, 0x1000
	v_mfma_f32_32x32x16_bf16 v[16:31], v[140:143], v[226:229], v[16:31]
	v_mfma_f32_32x32x16_bf16 v[0:15], v[140:143], v[230:233], v[0:15]
	global_load_lds_dwordx4 v254, s[28:29]
	s_add_u32 m0, m0, 0x1000
	v_mfma_f32_32x32x16_bf16 v[48:63], v[234:237], v[238:241], v[48:63]
	v_mfma_f32_32x32x16_bf16 v[32:47], v[234:237], v[242:245], v[32:47]
	global_load_lds_dwordx4 v254, s[30:31]
	s_add_u32 m0, m0, 0x1000
	v_mfma_f32_32x32x16_bf16 v[16:31], v[234:237], v[246:249], v[16:31]
	v_mfma_f32_32x32x16_bf16 v[0:15], v[234:237], v[250:253], v[0:15]
	global_load_lds_dwordx4 v254, s[34:35]
	s_setprio 0
	v_add_u32_e32 v254, 0x80, v254
	s_waitcnt vmcnt(8)
	s_barrier
	ds_read_b128 v[64:67], v110 offset:32768
	ds_read_b128 v[68:71], v111 offset:49152
	ds_read_b128 v[72:75], v111 offset:53248
	ds_read_b128 v[82:85], v111 offset:57344
	ds_read_b128 v[86:89], v111 offset:61440
	ds_read_b128 v[120:123], v112 offset:32768
	ds_read_b128 v[124:127], v113 offset:49152
	ds_read_b128 v[128:131], v113 offset:53248
	ds_read_b128 v[132:135], v113 offset:57344
	ds_read_b128 v[136:139], v113 offset:61440
	ds_read_b128 v[140:143], v114 offset:32768
	ds_read_b128 v[218:221], v115 offset:49152
	ds_read_b128 v[222:225], v115 offset:53248
	ds_read_b128 v[226:229], v115 offset:57344
	ds_read_b128 v[230:233], v115 offset:61440
	ds_read_b128 v[234:237], v116 offset:32768
	ds_read_b128 v[238:241], v117 offset:49152
	ds_read_b128 v[242:245], v117 offset:53248
	ds_read_b128 v[246:249], v117 offset:57344
	ds_read_b128 v[250:253], v117 offset:61440
	s_waitcnt lgkmcnt(0)
	s_barrier
	s_add_u32 m0, s36, 0x8000
	s_setprio 1
	v_mfma_f32_32x32x16_bf16 v[48:63], v[64:67], v[68:71], v[48:63]
	v_add_f32_e32 v144, v144, v145
	v_add_f32_e32 v146, v146, v147
	v_mfma_f32_32x32x16_bf16 v[32:47], v[64:67], v[72:75], v[32:47]
	v_add_f32_e32 v148, v148, v149
	v_add_f32_e32 v150, v150, v151
	global_load_lds_dwordx4 v254, s[18:19]
	s_add_u32 m0, m0, 0x1000
	v_mfma_f32_32x32x16_bf16 v[16:31], v[64:67], v[82:85], v[16:31]
	v_add_f32_e32 v144, v144, v146
	v_add_f32_e32 v148, v148, v150
	v_mfma_f32_32x32x16_bf16 v[0:15], v[64:67], v[86:89], v[0:15]
	v_add_f32_e32 v144, v144, v148
	v_fmamk_f32 v144, v144, 0x3a800000, v118
	global_load_lds_dwordx4 v254, s[20:21]
	s_add_u32 m0, m0, 0x1000
	v_mfma_f32_32x32x16_bf16 v[48:63], v[120:123], v[124:127], v[48:63]
	v_rsq_f32_e32 v144, v144
	s_nop 1
	v_mfma_f32_32x32x16_bf16 v[32:47], v[120:123], v[128:131], v[32:47]
	ds_bpermute_b32 v156, v153, v144
	ds_bpermute_b32 v157, v153, v144 offset:4
	global_load_lds_dwordx4 v254, s[22:23]
	s_add_u32 m0, m0, 0x1000
	v_mfma_f32_32x32x16_bf16 v[16:31], v[120:123], v[132:135], v[16:31]
	ds_bpermute_b32 v158, v153, v144 offset:8
	ds_bpermute_b32 v159, v153, v144 offset:12
	v_mfma_f32_32x32x16_bf16 v[0:15], v[120:123], v[136:139], v[0:15]
	ds_bpermute_b32 v160, v153, v144 offset:32
	ds_bpermute_b32 v161, v153, v144 offset:36
	global_load_lds_dwordx4 v254, s[24:25]
	s_add_u32 m0, m0, 0x1000
	v_mfma_f32_32x32x16_bf16 v[48:63], v[140:143], v[218:221], v[48:63]
	ds_bpermute_b32 v162, v153, v144 offset:40
	ds_bpermute_b32 v163, v153, v144 offset:44
	v_mfma_f32_32x32x16_bf16 v[32:47], v[140:143], v[222:225], v[32:47]
	ds_bpermute_b32 v164, v153, v144 offset:64
	ds_bpermute_b32 v165, v153, v144 offset:68
	global_load_lds_dwordx4 v254, s[26:27]
	s_add_u32 m0, m0, 0x1000
	v_mfma_f32_32x32x16_bf16 v[16:31], v[140:143], v[226:229], v[16:31]
	ds_bpermute_b32 v166, v153, v144 offset:72
	ds_bpermute_b32 v167, v153, v144 offset:76
	v_mfma_f32_32x32x16_bf16 v[0:15], v[140:143], v[230:233], v[0:15]
	ds_bpermute_b32 v168, v153, v144 offset:96
	ds_bpermute_b32 v169, v153, v144 offset:100
	global_load_lds_dwordx4 v254, s[28:29]
	s_add_u32 m0, m0, 0x1000
	v_mfma_f32_32x32x16_bf16 v[48:63], v[234:237], v[238:241], v[48:63]
	ds_bpermute_b32 v170, v153, v144 offset:104
	ds_bpermute_b32 v171, v153, v144 offset:108
	v_mfma_f32_32x32x16_bf16 v[32:47], v[234:237], v[242:245], v[32:47]
	global_load_lds_dwordx4 v254, s[30:31]
	s_add_u32 m0, m0, 0x1000
	v_mfma_f32_32x32x16_bf16 v[16:31], v[234:237], v[246:249], v[16:31]
	v_mfma_f32_32x32x16_bf16 v[0:15], v[234:237], v[250:253], v[0:15]
	global_load_lds_dwordx4 v254, s[34:35]
	s_setprio 0
	v_add_u32_e32 v254, 0x80, v254
	s_branch .LBB0_1373

.LBB0_1450:
	v_add_u32_e32 v82, s62, v95
	v_and_b32_e32 v226, 31, v199
	v_bfe_u32 v227, v199, 5, 1
	v_lshlrev_b32_e32 v229, 2, v227
	v_sub_u32_e32 v226, v226, v229
	v_add_u32_e32 v229, s62, v95
	v_add_lshl_u32 v226, v226, v229, 2
	v_lshlrev_b32_e32 v227, 4, v227
	global_load_dword v218, v226, s[6:7]
	v_add_u32_e32 v229, 0x10000, v226
	global_load_dword v219, v229, s[6:7]
	v_add_u32_e32 v229, 0x20000, v226
	global_load_dword v220, v229, s[6:7]
	v_add_u32_e32 v229, 0x30000, v226
	global_load_dword v221, v229, s[6:7]
	v_add_u32_e32 v229, 0x40000, v226
	global_load_dword v222, v229, s[6:7]
	v_add_u32_e32 v229, 0x50000, v226
	global_load_dword v223, v229, s[6:7]
	v_add_u32_e32 v229, 0x60000, v226
	global_load_dword v224, v229, s[6:7]
	v_add_u32_e32 v229, 0x70000, v226
	global_load_dword v225, v229, s[6:7]
	s_waitcnt vmcnt(0)
	v_add_f32_e32 v218, v218, v219
	v_add_f32_e32 v220, v220, v221
	v_add_f32_e32 v222, v222, v223
	v_add_f32_e32 v224, v224, v225
	v_add_f32_e32 v218, v218, v220
	v_add_f32_e32 v222, v222, v224
	v_add_f32_e32 v218, v218, v222
	v_fmamk_f32 v218, v218, 0x3a800000, v121
	v_rsq_f32_e32 v218, v218
	s_nop 1
	ds_bpermute_b32 v230, v227, v218
	ds_bpermute_b32 v231, v227, v218 offset:4
	ds_bpermute_b32 v232, v227, v218 offset:8
	ds_bpermute_b32 v233, v227, v218 offset:12
	ds_bpermute_b32 v234, v227, v218 offset:32
	ds_bpermute_b32 v235, v227, v218 offset:36
	ds_bpermute_b32 v236, v227, v218 offset:40
	ds_bpermute_b32 v237, v227, v218 offset:44
	ds_bpermute_b32 v238, v227, v218 offset:64
	ds_bpermute_b32 v239, v227, v218 offset:68
	ds_bpermute_b32 v240, v227, v218 offset:72
	ds_bpermute_b32 v241, v227, v218 offset:76
	ds_bpermute_b32 v242, v227, v218 offset:96
	ds_bpermute_b32 v243, v227, v218 offset:100
	ds_bpermute_b32 v244, v227, v218 offset:104
	ds_bpermute_b32 v245, v227, v218 offset:108
	s_waitcnt lgkmcnt(0)
	v_or_b32_e32 v84, 8, v82
	s_add_i32 s61, s62, 0xffffe000
	s_lshr_b32 s61, s61, 12
	s_mulk_i32 s61, 0xc00
	s_addk_i32 s61, 0xc00
	s_cmp_gt_i32 s4, 63
	s_cselect_b32 s4, s61, 0
	s_lshl_b64 s[62:63], s[4:5], 2
	s_add_u32 s62, s10, s62
	s_addc_u32 s63, s11, s63
	v_or_b32_e32 v123, 1, v82
	v_or_b32_e32 v125, 2, v82
	v_or_b32_e32 v127, 3, v82
	s_cmp_gt_i32 s77, 63
	v_or_b32_e32 v86, 16, v82
	v_or_b32_e32 v68, 9, v82
	v_or_b32_e32 v88, 17, v82
	v_or_b32_e32 v90, 24, v82
	v_ashrrev_i32_e32 v91, 31, v90
	v_lshl_add_u64 v[92:93], v[90:91], 2, s[6:7]
	v_add_co_u32_e32 v92, vcc, s76, v92
	s_nop 1
	v_addc_co_u32_e32 v93, vcc, 0, v93, vcc
	v_or_b32_e32 v92, 25, v82
	v_or_b32_e32 v129, 10, v82
	v_or_b32_e32 v130, 11, v82
	v_or_b32_e32 v131, 18, v82
	v_or_b32_e32 v132, 19, v82
	v_or_b32_e32 v133, 26, v82
	v_or_b32_e32 v64, s60, v94
	v_ashrrev_i32_e32 v65, 31, v64
	v_lshl_add_u64 v[70:71], v[64:65], 2, s[62:63]
	global_load_dword v69, v[70:71], off
	global_load_dword v67, v[70:71], off offset:128
	s_mov_b64 s[62:63], -1
	global_load_dword v66, v[70:71], off offset:256
	global_load_dword v65, v[70:71], off offset:384
	v_mov_b32_e32 v137, v231
	v_mov_b32_e32 v138, v232
	v_mov_b32_e32 v139, v233
	v_mov_b32_e32 v140, v234
	v_mov_b32_e32 v141, v235
	v_mov_b32_e32 v142, v236
	v_mov_b32_e32 v143, v237
	v_mov_b32_e32 v144, v238
	v_mov_b32_e32 v145, v239
	v_mov_b32_e32 v146, v240
	v_mov_b32_e32 v147, v241
	v_mov_b32_e32 v148, v242
	v_mov_b32_e32 v149, v243
	v_mov_b32_e32 v150, v244
	v_mov_b32_e32 v136, v230
	v_mov_b32_e32 v128, v245
	v_or_b32_e32 v134, 27, v82
	s_waitcnt vmcnt(3)
	v_fma_f32 v126, v48, v136, v69
	v_fma_f32 v124, v49, v137, v69
	v_fma_f32 v122, v50, v138, v69
	v_fma_f32 v93, v51, v139, v69
	v_fma_f32 v91, v52, v140, v69
	v_fma_f32 v89, v53, v141, v69
	v_fma_f32 v87, v54, v142, v69
	v_fma_f32 v85, v55, v143, v69
	v_fma_f32 v83, v56, v144, v69
	v_fma_f32 v75, v57, v145, v69
	v_fma_f32 v74, v58, v146, v69
	v_fma_f32 v73, v59, v147, v69
	v_fma_f32 v72, v60, v148, v69
	v_fma_f32 v71, v61, v149, v69
	v_fma_f32 v70, v62, v150, v69
	v_fmac_f32_e32 v69, v63, v128
	s_waitcnt vmcnt(2)
	v_fma_f32 v62, v32, v136, v67
	v_fma_f32 v61, v33, v137, v67
	v_fma_f32 v60, v34, v138, v67
	v_fma_f32 v59, v35, v139, v67
	v_fma_f32 v58, v36, v140, v67
	v_fma_f32 v57, v37, v141, v67
	v_fma_f32 v56, v38, v142, v67
	v_fma_f32 v55, v39, v143, v67
	v_fma_f32 v54, v40, v144, v67
	v_fma_f32 v53, v41, v145, v67
	v_fma_f32 v52, v42, v146, v67
	v_fma_f32 v51, v43, v147, v67
	v_fma_f32 v50, v44, v148, v67
	v_fma_f32 v49, v45, v149, v67
	v_fma_f32 v48, v46, v150, v67
	v_fmac_f32_e32 v67, v47, v128
	s_waitcnt vmcnt(1)
	v_fma_f32 v47, v16, v136, v66
	v_fma_f32 v46, v17, v137, v66
	v_fma_f32 v45, v18, v138, v66
	v_fma_f32 v44, v19, v139, v66
	v_fma_f32 v43, v20, v140, v66
	v_fma_f32 v42, v21, v141, v66
	v_fma_f32 v41, v22, v142, v66
	v_fma_f32 v40, v23, v143, v66
	v_fma_f32 v39, v24, v144, v66
	v_fma_f32 v38, v25, v145, v66
	v_fma_f32 v37, v26, v146, v66
	v_fma_f32 v36, v27, v147, v66
	v_fma_f32 v35, v28, v148, v66
	v_fma_f32 v34, v29, v149, v66
	v_fma_f32 v33, v30, v150, v66
	v_fmac_f32_e32 v66, v31, v128
	s_waitcnt vmcnt(0)
	v_fma_f32 v30, v0, v136, v65
	v_fma_f32 v29, v1, v137, v65
	v_fma_f32 v26, v2, v138, v65
	v_fma_f32 v25, v3, v139, v65
	v_fma_f32 v22, v4, v140, v65
	v_fma_f32 v21, v5, v141, v65
	v_fma_f32 v19, v6, v142, v65
	v_fma_f32 v18, v7, v143, v65
	v_fma_f32 v17, v8, v144, v65
	v_fma_f32 v16, v9, v145, v65
	v_fma_f32 v9, v10, v146, v65
	v_fma_f32 v8, v11, v147, v65
	v_fma_f32 v5, v12, v148, v65
	v_fma_f32 v4, v13, v149, v65
	v_fma_f32 v1, v14, v150, v65
	v_lshlrev_b32_e32 v32, 10, v82
	v_lshlrev_b32_e32 v31, 10, v123
	v_lshlrev_b32_e32 v28, 10, v125
	v_lshlrev_b32_e32 v27, 10, v127
	v_lshlrev_b32_e32 v24, 10, v84
	v_lshlrev_b32_e32 v23, 10, v68
	v_lshlrev_b32_e32 v20, 10, v129
	v_lshlrev_b32_e32 v14, 10, v130
	v_lshlrev_b32_e32 v13, 10, v86
	v_lshlrev_b32_e32 v12, 10, v88
	v_lshlrev_b32_e32 v11, 10, v131
	v_lshlrev_b32_e32 v10, 10, v132
	v_lshlrev_b32_e32 v7, 10, v90
	v_lshlrev_b32_e32 v6, 10, v92
	v_lshlrev_b32_e32 v3, 10, v133
	v_lshlrev_b32_e32 v2, 10, v134
	s_cbranch_scc0 .LBB0_1452
	v_add_u32_e32 v0, s60, v96
	v_add_u32_e32 v130, v32, v0
	v_ashrrev_i32_e32 v131, 31, v130
	v_cvt_pk_bf16_f32 v63, v126, s0
	v_lshl_add_u64 v[130:131], v[130:131], 1, s[8:9]
	global_store_short v[130:131], v63, off sc1
	v_add_u32_e32 v130, v31, v0
	v_ashrrev_i32_e32 v131, 31, v130
	v_cvt_pk_bf16_f32 v63, v124, s0
	v_lshl_add_u64 v[130:131], v[130:131], 1, s[8:9]
	global_store_short v[130:131], v63, off sc1
	v_add_u32_e32 v130, v28, v0
	v_ashrrev_i32_e32 v131, 31, v130
	v_cvt_pk_bf16_f32 v63, v122, s0
	v_lshl_add_u64 v[130:131], v[130:131], 1, s[8:9]
	global_store_short v[130:131], v63, off sc1
	v_add_u32_e32 v130, v27, v0
	v_ashrrev_i32_e32 v131, 31, v130
	v_cvt_pk_bf16_f32 v63, v93, s0
	v_lshl_add_u64 v[130:131], v[130:131], 1, s[8:9]
	global_store_short v[130:131], v63, off sc1
	v_add_u32_e32 v130, v24, v0
	v_ashrrev_i32_e32 v131, 31, v130
	v_cvt_pk_bf16_f32 v63, v91, s0
	v_lshl_add_u64 v[130:131], v[130:131], 1, s[8:9]
	global_store_short v[130:131], v63, off sc1
	v_add_u32_e32 v130, v23, v0
	v_ashrrev_i32_e32 v131, 31, v130
	v_cvt_pk_bf16_f32 v63, v89, s0
	v_lshl_add_u64 v[130:131], v[130:131], 1, s[8:9]
	global_store_short v[130:131], v63, off sc1
	v_add_u32_e32 v130, v20, v0
	v_ashrrev_i32_e32 v131, 31, v130
	v_cvt_pk_bf16_f32 v63, v87, s0
	v_lshl_add_u64 v[130:131], v[130:131], 1, s[8:9]
	global_store_short v[130:131], v63, off sc1
	v_add_u32_e32 v130, v14, v0
	v_ashrrev_i32_e32 v131, 31, v130
	v_cvt_pk_bf16_f32 v63, v85, s0
	v_lshl_add_u64 v[130:131], v[130:131], 1, s[8:9]
	global_store_short v[130:131], v63, off sc1
	v_add_u32_e32 v130, v13, v0
	v_ashrrev_i32_e32 v131, 31, v130
	v_cvt_pk_bf16_f32 v63, v83, s0
	v_lshl_add_u64 v[130:131], v[130:131], 1, s[8:9]
	global_store_short v[130:131], v63, off sc1
	v_add_u32_e32 v130, v12, v0
	v_ashrrev_i32_e32 v131, 31, v130
	v_cvt_pk_bf16_f32 v63, v75, s0
	v_lshl_add_u64 v[130:131], v[130:131], 1, s[8:9]
	global_store_short v[130:131], v63, off sc1
	v_add_u32_e32 v130, v11, v0
	v_ashrrev_i32_e32 v131, 31, v130
	v_cvt_pk_bf16_f32 v63, v74, s0
	v_lshl_add_u64 v[130:131], v[130:131], 1, s[8:9]
	global_store_short v[130:131], v63, off sc1
	v_add_u32_e32 v130, v10, v0
	v_ashrrev_i32_e32 v131, 31, v130
	v_cvt_pk_bf16_f32 v63, v73, s0
	v_lshl_add_u64 v[130:131], v[130:131], 1, s[8:9]
	global_store_short v[130:131], v63, off sc1
	v_add_u32_e32 v130, v7, v0
	v_ashrrev_i32_e32 v131, 31, v130
	v_cvt_pk_bf16_f32 v63, v72, s0
	v_lshl_add_u64 v[130:131], v[130:131], 1, s[8:9]
	global_store_short v[130:131], v63, off sc1
	v_add_u32_e32 v130, v6, v0
	v_ashrrev_i32_e32 v131, 31, v130
	v_cvt_pk_bf16_f32 v63, v71, s0
	v_lshl_add_u64 v[130:131], v[130:131], 1, s[8:9]
	global_store_short v[130:131], v63, off sc1
	v_add_u32_e32 v130, v3, v0
	v_ashrrev_i32_e32 v131, 31, v130
	v_cvt_pk_bf16_f32 v63, v70, s0
	v_lshl_add_u64 v[130:131], v[130:131], 1, s[8:9]
	global_store_short v[130:131], v63, off sc1
	v_add_u32_e32 v130, v2, v0
	v_ashrrev_i32_e32 v131, 31, v130
	v_cvt_pk_bf16_f32 v63, v69, s0
	v_lshl_add_u64 v[130:131], v[130:131], 1, s[8:9]
	global_store_short v[130:131], v63, off sc1
	v_or_b32_e32 v63, 32, v0
	v_add_u32_e32 v130, v32, v63
	v_ashrrev_i32_e32 v131, 31, v130
	v_cvt_pk_bf16_f32 v68, v62, s0
	v_lshl_add_u64 v[130:131], v[130:131], 1, s[8:9]
	global_store_short v[130:131], v68, off sc1
	v_add_u32_e32 v130, v31, v63
	v_ashrrev_i32_e32 v131, 31, v130
	v_cvt_pk_bf16_f32 v68, v61, s0
	v_lshl_add_u64 v[130:131], v[130:131], 1, s[8:9]
	global_store_short v[130:131], v68, off sc1
	v_add_u32_e32 v130, v28, v63
	v_ashrrev_i32_e32 v131, 31, v130
	v_cvt_pk_bf16_f32 v68, v60, s0
	v_lshl_add_u64 v[130:131], v[130:131], 1, s[8:9]
	global_store_short v[130:131], v68, off sc1
	v_add_u32_e32 v130, v27, v63
	v_ashrrev_i32_e32 v131, 31, v130
	v_cvt_pk_bf16_f32 v68, v59, s0
	v_lshl_add_u64 v[130:131], v[130:131], 1, s[8:9]
	global_store_short v[130:131], v68, off sc1
	v_add_u32_e32 v130, v24, v63
	v_ashrrev_i32_e32 v131, 31, v130
	v_cvt_pk_bf16_f32 v68, v58, s0
	v_lshl_add_u64 v[130:131], v[130:131], 1, s[8:9]
	global_store_short v[130:131], v68, off sc1
	v_add_u32_e32 v130, v23, v63
	v_ashrrev_i32_e32 v131, 31, v130
	v_cvt_pk_bf16_f32 v68, v57, s0
	v_lshl_add_u64 v[130:131], v[130:131], 1, s[8:9]
	global_store_short v[130:131], v68, off sc1
	v_add_u32_e32 v130, v20, v63
	v_ashrrev_i32_e32 v131, 31, v130
	v_cvt_pk_bf16_f32 v68, v56, s0
	v_lshl_add_u64 v[130:131], v[130:131], 1, s[8:9]
	global_store_short v[130:131], v68, off sc1
	v_add_u32_e32 v130, v14, v63
	v_ashrrev_i32_e32 v131, 31, v130
	v_cvt_pk_bf16_f32 v68, v55, s0
	v_lshl_add_u64 v[130:131], v[130:131], 1, s[8:9]
	global_store_short v[130:131], v68, off sc1
	v_add_u32_e32 v130, v13, v63
	v_ashrrev_i32_e32 v131, 31, v130
	v_cvt_pk_bf16_f32 v68, v54, s0
	v_lshl_add_u64 v[130:131], v[130:131], 1, s[8:9]
	global_store_short v[130:131], v68, off sc1
	v_add_u32_e32 v130, v12, v63
	v_ashrrev_i32_e32 v131, 31, v130
	v_cvt_pk_bf16_f32 v68, v53, s0
	v_lshl_add_u64 v[130:131], v[130:131], 1, s[8:9]
	global_store_short v[130:131], v68, off sc1
	v_add_u32_e32 v130, v11, v63
	v_ashrrev_i32_e32 v131, 31, v130
	v_cvt_pk_bf16_f32 v68, v52, s0
	v_lshl_add_u64 v[130:131], v[130:131], 1, s[8:9]
	global_store_short v[130:131], v68, off sc1
	v_add_u32_e32 v130, v10, v63
	v_ashrrev_i32_e32 v131, 31, v130
	v_cvt_pk_bf16_f32 v68, v51, s0
	v_lshl_add_u64 v[130:131], v[130:131], 1, s[8:9]
	global_store_short v[130:131], v68, off sc1
	v_add_u32_e32 v130, v7, v63
	v_ashrrev_i32_e32 v131, 31, v130
	v_cvt_pk_bf16_f32 v68, v50, s0
	v_lshl_add_u64 v[130:131], v[130:131], 1, s[8:9]
	global_store_short v[130:131], v68, off sc1
	v_add_u32_e32 v130, v6, v63
	v_ashrrev_i32_e32 v131, 31, v130
	v_cvt_pk_bf16_f32 v68, v49, s0
	v_lshl_add_u64 v[130:131], v[130:131], 1, s[8:9]
	global_store_short v[130:131], v68, off sc1
	v_add_u32_e32 v130, v3, v63
	v_ashrrev_i32_e32 v131, 31, v130
	v_cvt_pk_bf16_f32 v68, v48, s0
	v_lshl_add_u64 v[130:131], v[130:131], 1, s[8:9]
	global_store_short v[130:131], v68, off sc1
	v_add_u32_e32 v130, v2, v63
	v_ashrrev_i32_e32 v131, 31, v130
	v_cvt_pk_bf16_f32 v68, v67, s0
	v_lshl_add_u64 v[130:131], v[130:131], 1, s[8:9]
	v_or_b32_e32 v63, 64, v0
	global_store_short v[130:131], v68, off sc1
	v_add_u32_e32 v130, v32, v63
	v_ashrrev_i32_e32 v131, 31, v130
	v_cvt_pk_bf16_f32 v68, v47, s0
	v_lshl_add_u64 v[130:131], v[130:131], 1, s[8:9]
	global_store_short v[130:131], v68, off sc1
	v_add_u32_e32 v130, v31, v63
	v_ashrrev_i32_e32 v131, 31, v130
	v_cvt_pk_bf16_f32 v68, v46, s0
	v_lshl_add_u64 v[130:131], v[130:131], 1, s[8:9]
	global_store_short v[130:131], v68, off sc1
	v_add_u32_e32 v130, v28, v63
	v_ashrrev_i32_e32 v131, 31, v130
	v_cvt_pk_bf16_f32 v68, v45, s0
	v_lshl_add_u64 v[130:131], v[130:131], 1, s[8:9]
	global_store_short v[130:131], v68, off sc1
	v_add_u32_e32 v130, v27, v63
	v_ashrrev_i32_e32 v131, 31, v130
	v_cvt_pk_bf16_f32 v68, v44, s0
	v_lshl_add_u64 v[130:131], v[130:131], 1, s[8:9]
	global_store_short v[130:131], v68, off sc1
	v_add_u32_e32 v130, v24, v63
	v_ashrrev_i32_e32 v131, 31, v130
	v_cvt_pk_bf16_f32 v68, v43, s0
	v_lshl_add_u64 v[130:131], v[130:131], 1, s[8:9]
	global_store_short v[130:131], v68, off sc1
	v_add_u32_e32 v130, v23, v63
	v_ashrrev_i32_e32 v131, 31, v130
	v_cvt_pk_bf16_f32 v68, v42, s0
	v_lshl_add_u64 v[130:131], v[130:131], 1, s[8:9]
	global_store_short v[130:131], v68, off sc1
	v_add_u32_e32 v130, v20, v63
	v_ashrrev_i32_e32 v131, 31, v130
	v_cvt_pk_bf16_f32 v68, v41, s0
	v_lshl_add_u64 v[130:131], v[130:131], 1, s[8:9]
	global_store_short v[130:131], v68, off sc1
	v_add_u32_e32 v130, v14, v63
	v_ashrrev_i32_e32 v131, 31, v130
	v_cvt_pk_bf16_f32 v68, v40, s0
	v_lshl_add_u64 v[130:131], v[130:131], 1, s[8:9]
	global_store_short v[130:131], v68, off sc1
	v_add_u32_e32 v130, v13, v63
	v_ashrrev_i32_e32 v131, 31, v130
	v_cvt_pk_bf16_f32 v68, v39, s0
	v_lshl_add_u64 v[130:131], v[130:131], 1, s[8:9]
	global_store_short v[130:131], v68, off sc1
	v_add_u32_e32 v130, v12, v63
	v_ashrrev_i32_e32 v131, 31, v130
	v_cvt_pk_bf16_f32 v68, v38, s0
	v_lshl_add_u64 v[130:131], v[130:131], 1, s[8:9]
	global_store_short v[130:131], v68, off sc1
	v_add_u32_e32 v130, v11, v63
	v_ashrrev_i32_e32 v131, 31, v130
	v_cvt_pk_bf16_f32 v68, v37, s0
	v_lshl_add_u64 v[130:131], v[130:131], 1, s[8:9]
	global_store_short v[130:131], v68, off sc1
	v_add_u32_e32 v130, v10, v63
	v_ashrrev_i32_e32 v131, 31, v130
	v_cvt_pk_bf16_f32 v68, v36, s0
	v_lshl_add_u64 v[130:131], v[130:131], 1, s[8:9]
	global_store_short v[130:131], v68, off sc1
	v_add_u32_e32 v130, v7, v63
	v_ashrrev_i32_e32 v131, 31, v130
	v_cvt_pk_bf16_f32 v68, v35, s0
	v_lshl_add_u64 v[130:131], v[130:131], 1, s[8:9]
	global_store_short v[130:131], v68, off sc1
	v_add_u32_e32 v130, v6, v63
	v_ashrrev_i32_e32 v131, 31, v130
	v_cvt_pk_bf16_f32 v68, v34, s0
	v_lshl_add_u64 v[130:131], v[130:131], 1, s[8:9]
	global_store_short v[130:131], v68, off sc1
	v_add_u32_e32 v130, v3, v63
	v_ashrrev_i32_e32 v131, 31, v130
	v_cvt_pk_bf16_f32 v68, v33, s0
	v_lshl_add_u64 v[130:131], v[130:131], 1, s[8:9]
	global_store_short v[130:131], v68, off sc1
	v_add_u32_e32 v130, v2, v63
	v_ashrrev_i32_e32 v131, 31, v130
	v_cvt_pk_bf16_f32 v68, v66, s0
	v_lshl_add_u64 v[130:131], v[130:131], 1, s[8:9]
	v_or_b32_e32 v0, 0x60, v0
	global_store_short v[130:131], v68, off sc1
	v_add_u32_e32 v130, v32, v0
	v_ashrrev_i32_e32 v131, 31, v130
	v_cvt_pk_bf16_f32 v63, v30, s0
	v_lshl_add_u64 v[130:131], v[130:131], 1, s[8:9]
	global_store_short v[130:131], v63, off sc1
	v_add_u32_e32 v130, v31, v0
	v_ashrrev_i32_e32 v131, 31, v130
	v_cvt_pk_bf16_f32 v63, v29, s0
	v_lshl_add_u64 v[130:131], v[130:131], 1, s[8:9]
	global_store_short v[130:131], v63, off sc1
	v_add_u32_e32 v130, v28, v0
	v_ashrrev_i32_e32 v131, 31, v130
	v_cvt_pk_bf16_f32 v63, v26, s0
	v_lshl_add_u64 v[130:131], v[130:131], 1, s[8:9]
	global_store_short v[130:131], v63, off sc1
	v_add_u32_e32 v130, v27, v0
	v_ashrrev_i32_e32 v131, 31, v130
	v_cvt_pk_bf16_f32 v63, v25, s0
	v_lshl_add_u64 v[130:131], v[130:131], 1, s[8:9]
	global_store_short v[130:131], v63, off sc1
	v_add_u32_e32 v130, v24, v0
	v_ashrrev_i32_e32 v131, 31, v130
	v_cvt_pk_bf16_f32 v63, v22, s0
	v_lshl_add_u64 v[130:131], v[130:131], 1, s[8:9]
	global_store_short v[130:131], v63, off sc1
	v_add_u32_e32 v130, v23, v0
	v_ashrrev_i32_e32 v131, 31, v130
	v_cvt_pk_bf16_f32 v63, v21, s0
	v_lshl_add_u64 v[130:131], v[130:131], 1, s[8:9]
	global_store_short v[130:131], v63, off sc1
	v_add_u32_e32 v130, v20, v0
	v_ashrrev_i32_e32 v131, 31, v130
	v_cvt_pk_bf16_f32 v63, v19, s0
	v_lshl_add_u64 v[130:131], v[130:131], 1, s[8:9]
	global_store_short v[130:131], v63, off sc1
	v_add_u32_e32 v130, v14, v0
	v_ashrrev_i32_e32 v131, 31, v130
	v_cvt_pk_bf16_f32 v63, v18, s0
	v_lshl_add_u64 v[130:131], v[130:131], 1, s[8:9]
	global_store_short v[130:131], v63, off sc1
	v_add_u32_e32 v130, v13, v0
	v_ashrrev_i32_e32 v131, 31, v130
	v_cvt_pk_bf16_f32 v63, v17, s0
	v_lshl_add_u64 v[130:131], v[130:131], 1, s[8:9]
	global_store_short v[130:131], v63, off sc1
	v_add_u32_e32 v130, v12, v0
	v_ashrrev_i32_e32 v131, 31, v130
	v_cvt_pk_bf16_f32 v63, v16, s0
	v_lshl_add_u64 v[130:131], v[130:131], 1, s[8:9]
	global_store_short v[130:131], v63, off sc1
	v_add_u32_e32 v130, v11, v0
	v_ashrrev_i32_e32 v131, 31, v130
	v_cvt_pk_bf16_f32 v63, v9, s0
	v_lshl_add_u64 v[130:131], v[130:131], 1, s[8:9]
	global_store_short v[130:131], v63, off sc1
	v_add_u32_e32 v130, v10, v0
	v_ashrrev_i32_e32 v131, 31, v130
	v_cvt_pk_bf16_f32 v63, v8, s0
	v_lshl_add_u64 v[130:131], v[130:131], 1, s[8:9]
	global_store_short v[130:131], v63, off sc1
	v_add_u32_e32 v130, v7, v0
	v_ashrrev_i32_e32 v131, 31, v130
	v_cvt_pk_bf16_f32 v63, v5, s0
	v_lshl_add_u64 v[130:131], v[130:131], 1, s[8:9]
	global_store_short v[130:131], v63, off sc1
	v_add_u32_e32 v130, v6, v0
	v_ashrrev_i32_e32 v131, 31, v130
	v_cvt_pk_bf16_f32 v63, v4, s0
	v_lshl_add_u64 v[130:131], v[130:131], 1, s[8:9]
	global_store_short v[130:131], v63, off sc1
	v_add_u32_e32 v130, v3, v0
	v_ashrrev_i32_e32 v131, 31, v130
	v_cvt_pk_bf16_f32 v63, v1, s0
	v_lshl_add_u64 v[130:131], v[130:131], 1, s[8:9]
	global_store_short v[130:131], v63, off sc1
	v_add_u32_e32 v0, v2, v0
	s_mov_b64 s[62:63], 0

.Lmap_done_3_pf_p25:
	s_lshl_b32 s44, s41, 7
	s_lshl_b32 s42, s50, 7
	s_ashr_i32 s45, s44, 31
	s_ashr_i32 s43, s42, 31
	s_lshl_b64 s[46:47], s[44:45], 11
	s_lshl_b64 s[48:49], s[42:43], 11
	s_lshl_b32 s38, s44, 11
	s_add_u32 s18, s14, s38
	s_addc_u32 s19, s15, 0
	s_add_u32 s18, s18, 0x679f000
	s_addc_u32 s19, s19, 0
	s_add_u32 s20, s18, 0x10000
	s_addc_u32 s21, s19, 0
	s_add_u32 s22, s20, 0x10000
	s_addc_u32 s23, s21, 0
	s_add_u32 s24, s22, 0x10000
	s_addc_u32 s25, s23, 0
	s_lshl_b32 s38, s42, 11
	s_add_u32 s26, s14, s38
	s_addc_u32 s27, s15, 0
	s_add_u32 s26, s26, 0x3aa0000
	s_addc_u32 s27, s27, 0
	s_add_u32 s28, s26, 0x10000
	s_addc_u32 s29, s27, 0
	s_add_u32 s30, s28, 0x10000
	s_addc_u32 s31, s29, 0
	s_add_u32 s34, s30, 0x10000
	s_addc_u32 s35, s31, 0
	v_mov_b32_e32 v254, v76
	s_mov_b32 s39, 1
	s_waitcnt vmcnt(8)
	s_barrier
	ds_read_b128 v[64:67], v110
	ds_read_b128 v[68:71], v111 offset:16384
	ds_read_b128 v[72:75], v111 offset:20480
	ds_read_b128 v[82:85], v111 offset:24576
	ds_read_b128 v[86:89], v111 offset:28672
	ds_read_b128 v[120:123], v112
	ds_read_b128 v[124:127], v113 offset:16384
	ds_read_b128 v[128:131], v113 offset:20480
	ds_read_b128 v[132:135], v113 offset:24576
	ds_read_b128 v[136:139], v113 offset:28672
	ds_read_b128 v[140:143], v114
	ds_read_b128 v[218:221], v115 offset:16384
	ds_read_b128 v[222:225], v115 offset:20480
	ds_read_b128 v[226:229], v115 offset:24576
	ds_read_b128 v[230:233], v115 offset:28672
	ds_read_b128 v[234:237], v116
	ds_read_b128 v[238:241], v117 offset:16384
	ds_read_b128 v[242:245], v117 offset:20480
	ds_read_b128 v[246:249], v117 offset:24576
	ds_read_b128 v[250:253], v117 offset:28672
	s_waitcnt lgkmcnt(0)
	s_barrier
	s_mov_b32 m0, s36
	s_setprio 1
	v_mfma_f32_32x32x16_bf16 v[48:63], v[64:67], v[68:71], v[48:63]
	v_mfma_f32_32x32x16_bf16 v[32:47], v[64:67], v[72:75], v[32:47]
	global_load_lds_dwordx4 v254, s[18:19]
	s_add_u32 m0, m0, 0x1000
	v_mfma_f32_32x32x16_bf16 v[16:31], v[64:67], v[82:85], v[16:31]
	v_mfma_f32_32x32x16_bf16 v[0:15], v[64:67], v[86:89], v[0:15]
	global_load_lds_dwordx4 v254, s[20:21]
	s_add_u32 m0, m0, 0x1000
	v_mfma_f32_32x32x16_bf16 v[48:63], v[120:123], v[124:127], v[48:63]
	v_mfma_f32_32x32x16_bf16 v[32:47], v[120:123], v[128:131], v[32:47]
	global_load_lds_dwordx4 v254, s[22:23]
	s_add_u32 m0, m0, 0x1000
	v_mfma_f32_32x32x16_bf16 v[16:31], v[120:123], v[132:135], v[16:31]
	v_mfma_f32_32x32x16_bf16 v[0:15], v[120:123], v[136:139], v[0:15]
	global_load_lds_dwordx4 v254, s[24:25]
	s_add_u32 m0, m0, 0x1000
	v_mfma_f32_32x32x16_bf16 v[48:63], v[140:143], v[218:221], v[48:63]
	v_mfma_f32_32x32x16_bf16 v[32:47], v[140:143], v[222:225], v[32:47]
	global_load_lds_dwordx4 v254, s[26:27]
	s_add_u32 m0, m0, 0x1000
	v_mfma_f32_32x32x16_bf16 v[16:31], v[140:143], v[226:229], v[16:31]
	v_mfma_f32_32x32x16_bf16 v[0:15], v[140:143], v[230:233], v[0:15]
	global_load_lds_dwordx4 v254, s[28:29]
	s_add_u32 m0, m0, 0x1000
	v_mfma_f32_32x32x16_bf16 v[48:63], v[234:237], v[238:241], v[48:63]
	v_mfma_f32_32x32x16_bf16 v[32:47], v[234:237], v[242:245], v[32:47]
	global_load_lds_dwordx4 v254, s[30:31]
	s_add_u32 m0, m0, 0x1000
	v_mfma_f32_32x32x16_bf16 v[16:31], v[234:237], v[246:249], v[16:31]
	v_mfma_f32_32x32x16_bf16 v[0:15], v[234:237], v[250:253], v[0:15]
	global_load_lds_dwordx4 v254, s[34:35]
	s_setprio 0
	v_add_u32_e32 v254, 0x80, v254
	s_waitcnt vmcnt(8)
	s_barrier
	ds_read_b128 v[64:67], v110 offset:32768
	ds_read_b128 v[68:71], v111 offset:49152
	ds_read_b128 v[72:75], v111 offset:53248
	ds_read_b128 v[82:85], v111 offset:57344
	ds_read_b128 v[86:89], v111 offset:61440
	ds_read_b128 v[120:123], v112 offset:32768
	ds_read_b128 v[124:127], v113 offset:49152
	ds_read_b128 v[128:131], v113 offset:53248
	ds_read_b128 v[132:135], v113 offset:57344
	ds_read_b128 v[136:139], v113 offset:61440
	ds_read_b128 v[140:143], v114 offset:32768
	ds_read_b128 v[218:221], v115 offset:49152
	ds_read_b128 v[222:225], v115 offset:53248
	ds_read_b128 v[226:229], v115 offset:57344
	ds_read_b128 v[230:233], v115 offset:61440
	ds_read_b128 v[234:237], v116 offset:32768
	ds_read_b128 v[238:241], v117 offset:49152
	ds_read_b128 v[242:245], v117 offset:53248
	ds_read_b128 v[246:249], v117 offset:57344
	ds_read_b128 v[250:253], v117 offset:61440
	s_waitcnt lgkmcnt(0)
	s_barrier
	s_add_u32 m0, s36, 0x8000
	s_setprio 1
	v_mfma_f32_32x32x16_bf16 v[48:63], v[64:67], v[68:71], v[48:63]
	v_add_f32_e32 v144, v144, v145
	v_add_f32_e32 v146, v146, v147
	v_mfma_f32_32x32x16_bf16 v[32:47], v[64:67], v[72:75], v[32:47]
	v_add_f32_e32 v148, v148, v149
	v_add_f32_e32 v150, v150, v151
	global_load_lds_dwordx4 v254, s[18:19]
	s_add_u32 m0, m0, 0x1000
	v_mfma_f32_32x32x16_bf16 v[16:31], v[64:67], v[82:85], v[16:31]
	v_add_f32_e32 v144, v144, v146
	v_add_f32_e32 v148, v148, v150
	v_mfma_f32_32x32x16_bf16 v[0:15], v[64:67], v[86:89], v[0:15]
	v_add_f32_e32 v144, v144, v148
	v_fmamk_f32 v144, v144, 0x3a800000, v118
	global_load_lds_dwordx4 v254, s[20:21]
	s_add_u32 m0, m0, 0x1000
	v_mfma_f32_32x32x16_bf16 v[48:63], v[120:123], v[124:127], v[48:63]
	v_rsq_f32_e32 v144, v144
	s_nop 1
	v_mfma_f32_32x32x16_bf16 v[32:47], v[120:123], v[128:131], v[32:47]
	ds_bpermute_b32 v156, v153, v144
	ds_bpermute_b32 v157, v153, v144 offset:4
	global_load_lds_dwordx4 v254, s[22:23]
	s_add_u32 m0, m0, 0x1000
	v_mfma_f32_32x32x16_bf16 v[16:31], v[120:123], v[132:135], v[16:31]
	ds_bpermute_b32 v158, v153, v144 offset:8
	ds_bpermute_b32 v159, v153, v144 offset:12
	v_mfma_f32_32x32x16_bf16 v[0:15], v[120:123], v[136:139], v[0:15]
	ds_bpermute_b32 v160, v153, v144 offset:32
	ds_bpermute_b32 v161, v153, v144 offset:36
	global_load_lds_dwordx4 v254, s[24:25]
	s_add_u32 m0, m0, 0x1000
	v_mfma_f32_32x32x16_bf16 v[48:63], v[140:143], v[218:221], v[48:63]
	ds_bpermute_b32 v162, v153, v144 offset:40
	ds_bpermute_b32 v163, v153, v144 offset:44
	v_mfma_f32_32x32x16_bf16 v[32:47], v[140:143], v[222:225], v[32:47]
	ds_bpermute_b32 v164, v153, v144 offset:64
	ds_bpermute_b32 v165, v153, v144 offset:68
	global_load_lds_dwordx4 v254, s[26:27]
	s_add_u32 m0, m0, 0x1000
	v_mfma_f32_32x32x16_bf16 v[16:31], v[140:143], v[226:229], v[16:31]
	ds_bpermute_b32 v166, v153, v144 offset:72
	ds_bpermute_b32 v167, v153, v144 offset:76
	v_mfma_f32_32x32x16_bf16 v[0:15], v[140:143], v[230:233], v[0:15]
	ds_bpermute_b32 v168, v153, v144 offset:96
	ds_bpermute_b32 v169, v153, v144 offset:100
	global_load_lds_dwordx4 v254, s[28:29]
	s_add_u32 m0, m0, 0x1000
	v_mfma_f32_32x32x16_bf16 v[48:63], v[234:237], v[238:241], v[48:63]
	ds_bpermute_b32 v170, v153, v144 offset:104
	ds_bpermute_b32 v171, v153, v144 offset:108
	v_mfma_f32_32x32x16_bf16 v[32:47], v[234:237], v[242:245], v[32:47]
	global_load_lds_dwordx4 v254, s[30:31]
	s_add_u32 m0, m0, 0x1000
	v_mfma_f32_32x32x16_bf16 v[16:31], v[234:237], v[246:249], v[16:31]
	v_mfma_f32_32x32x16_bf16 v[0:15], v[234:237], v[250:253], v[0:15]
	global_load_lds_dwordx4 v254, s[34:35]
	s_setprio 0
	v_add_u32_e32 v254, 0x80, v254
	s_branch .LBB0_1616
